# phase-0 modulation GEMV K loop rewritten by hand: 32 row loads in flight per wave with rolling refill, LDS operands double-buffered, same FMA order
# baseline (speedup 1.0000x reference)
; #define LAS __attribute__((address_space(3)))
; __device__ __forceinline__ void phase0(const Params& p, char* shm) {
;     ...
;       const int l = task / 96, col0 = (task % 96) * 128;
;       const int cp = (tid & 63) * 2, ks = tid >> 6;
;       const float* W = p.in[4] + ((size_t)l * 2048 + ks * 256) * NMOD6 + col0 + cp;
;       float a0[9], a1[9];
; #pragma unroll
;       for (int r = 0; r < 9; ++r) { a0[r] = 0.f; a1[r] = 0.f; }
;       const LAS float* condL = (const LAS float*)(LAS char*)shm;
;       for (int k = 0; k < 256; k += 32) {
;         f32x2 w[32];
; #pragma unroll
;         for (int u = 0; u < 32; ++u) w[u] = *(const f32x2*)(W + (size_t)(k + u) * NMOD6);
.LBB0_117:
	s_mul_hi_i32 s0, s76, 0x2aaaaaab
	s_lshr_b32 s1, s0, 31
	s_ashr_i32 s0, s0, 4
	s_add_i32 s20, s0, s1
	s_mul_i32 s0, s20, 0x60
	s_sub_i32 s0, s76, s0
	s_ashr_i32 s21, s20, 31
	s_lshl_b32 s22, s0, 7
	s_lshl_b64 s[0:1], s[20:21], 11
	v_lshl_add_u64 v[2:3], s[0:1], 0, v[76:77]
	v_mov_b64_e32 v[4:5], s[30:31]
	v_mad_u64_u32 v[4:5], s[0:1], v2, s65, v[4:5]
	v_mad_i32_i24 v5, v3, s65, v5
	s_ashr_i32 s23, s22, 31
	v_lshl_add_u64 v[2:3], s[22:23], 2, v[4:5]
	v_mov_b32_e32 v91, v47
	v_mov_b32_e32 v6, 0
	v_lshl_add_u64 v[100:101], v[2:3], 0, v[90:91]
	s_movk_i32 s0, 0xffe0
	v_mov_b32_e32 v89, v43
	v_mov_b32_e32 v7, v6
	v_mov_b32_e32 v18, v6
	v_mov_b32_e32 v19, v6
	v_mov_b32_e32 v16, v6
	v_mov_b32_e32 v17, v6
	v_mov_b32_e32 v8, v6
	v_mov_b32_e32 v9, v6
	v_mov_b32_e32 v20, v6
	v_mov_b32_e32 v21, v6
	v_mov_b32_e32 v22, v6
	v_mov_b32_e32 v23, v6
	v_mov_b32_e32 v40, v6
	v_mov_b32_e32 v41, v6
	v_mov_b32_e32 v120, v6
	v_mov_b32_e32 v121, v6
	v_mov_b32_e32 v122, v6
	v_mov_b32_e32 v123, v6
	v_readfirstlane_b32 s100, v100
	v_readfirstlane_b32 s101, v101
	s_nop 4
	v_subrev_u32_e32 v144, s100, v100
	global_load_dwordx2 v[182:183], v144, s[100:101]
	s_add_u32 s100, s100, 0xc000
	s_addc_u32 s101, s101, 0
	global_load_dwordx2 v[184:185], v144, s[100:101]
	s_add_u32 s100, s100, 0xc000
	s_addc_u32 s101, s101, 0
	global_load_dwordx2 v[186:187], v144, s[100:101]
	s_add_u32 s100, s100, 0xc000
	s_addc_u32 s101, s101, 0
	global_load_dwordx2 v[188:189], v144, s[100:101]
	s_add_u32 s100, s100, 0xc000
	s_addc_u32 s101, s101, 0
	global_load_dwordx2 v[190:191], v144, s[100:101]
	s_add_u32 s100, s100, 0xc000
	s_addc_u32 s101, s101, 0
	global_load_dwordx2 v[192:193], v144, s[100:101]
	s_add_u32 s100, s100, 0xc000
	s_addc_u32 s101, s101, 0
	global_load_dwordx2 v[194:195], v144, s[100:101]
	s_add_u32 s100, s100, 0xc000
	s_addc_u32 s101, s101, 0
	global_load_dwordx2 v[196:197], v144, s[100:101]
	s_add_u32 s100, s100, 0xc000
	s_addc_u32 s101, s101, 0
	global_load_dwordx2 v[198:199], v144, s[100:101]
	s_add_u32 s100, s100, 0xc000
	s_addc_u32 s101, s101, 0
	global_load_dwordx2 v[200:201], v144, s[100:101]
	s_add_u32 s100, s100, 0xc000
	s_addc_u32 s101, s101, 0
	global_load_dwordx2 v[202:203], v144, s[100:101]
	s_add_u32 s100, s100, 0xc000
	s_addc_u32 s101, s101, 0
	global_load_dwordx2 v[204:205], v144, s[100:101]
	s_add_u32 s100, s100, 0xc000
	s_addc_u32 s101, s101, 0
	global_load_dwordx2 v[206:207], v144, s[100:101]
	s_add_u32 s100, s100, 0xc000
	s_addc_u32 s101, s101, 0
	global_load_dwordx2 v[208:209], v144, s[100:101]
	s_add_u32 s100, s100, 0xc000
	s_addc_u32 s101, s101, 0
	global_load_dwordx2 v[210:211], v144, s[100:101]
	s_add_u32 s100, s100, 0xc000
	s_addc_u32 s101, s101, 0
	global_load_dwordx2 v[212:213], v144, s[100:101]
	s_add_u32 s100, s100, 0xc000
	s_addc_u32 s101, s101, 0
	global_load_dwordx2 v[214:215], v144, s[100:101]
	s_add_u32 s100, s100, 0xc000
	s_addc_u32 s101, s101, 0
	global_load_dwordx2 v[216:217], v144, s[100:101]
	s_add_u32 s100, s100, 0xc000
	s_addc_u32 s101, s101, 0
	global_load_dwordx2 v[218:219], v144, s[100:101]
	s_add_u32 s100, s100, 0xc000
	s_addc_u32 s101, s101, 0
	global_load_dwordx2 v[220:221], v144, s[100:101]
	s_add_u32 s100, s100, 0xc000
	s_addc_u32 s101, s101, 0
	global_load_dwordx2 v[222:223], v144, s[100:101]
	s_add_u32 s100, s100, 0xc000
	s_addc_u32 s101, s101, 0
	global_load_dwordx2 v[224:225], v144, s[100:101]
	s_add_u32 s100, s100, 0xc000
	s_addc_u32 s101, s101, 0
	global_load_dwordx2 v[226:227], v144, s[100:101]
	s_add_u32 s100, s100, 0xc000
	s_addc_u32 s101, s101, 0
	global_load_dwordx2 v[228:229], v144, s[100:101]
	s_add_u32 s100, s100, 0xc000
	s_addc_u32 s101, s101, 0
	global_load_dwordx2 v[230:231], v144, s[100:101]
	s_add_u32 s100, s100, 0xc000
	s_addc_u32 s101, s101, 0
	global_load_dwordx2 v[232:233], v144, s[100:101]
	s_add_u32 s100, s100, 0xc000
	s_addc_u32 s101, s101, 0
	global_load_dwordx2 v[234:235], v144, s[100:101]
	s_add_u32 s100, s100, 0xc000
	s_addc_u32 s101, s101, 0
	global_load_dwordx2 v[236:237], v144, s[100:101]
	s_add_u32 s100, s100, 0xc000
	s_addc_u32 s101, s101, 0
	global_load_dwordx2 v[238:239], v144, s[100:101]
	s_add_u32 s100, s100, 0xc000
	s_addc_u32 s101, s101, 0
	global_load_dwordx2 v[240:241], v144, s[100:101]
	s_add_u32 s100, s100, 0xc000
	s_addc_u32 s101, s101, 0
	global_load_dwordx2 v[242:243], v144, s[100:101]
	s_add_u32 s100, s100, 0xc000
	s_addc_u32 s101, s101, 0
	global_load_dwordx2 v[244:245], v144, s[100:101]
	s_add_u32 s100, s100, 0xc000
	s_addc_u32 s101, s101, 0
	v_add_u32_e32 v46, 0xffff0000, v89
	ds_read_b128 v[104:107], v46
	ds_read_b128 v[108:111], v46 offset:8192
	ds_read_b128 v[112:115], v46 offset:16384
	ds_read_b128 v[116:119], v46 offset:24576
	ds_read_b128 v[124:127], v46 offset:32768
	ds_read_b128 v[128:131], v46 offset:40960
	ds_read_b128 v[132:135], v46 offset:49152
	ds_read_b128 v[136:139], v46 offset:57344
	ds_read_b128 v[140:143], v89
	s_mov_b32 s0, 0
; #define LAS __attribute__((address_space(3)))
; __device__ __forceinline__ void phase0(const Params& p, char* shm) {
;     ...
;       for (int k = 0; k < 256; k += 32) {
;         f32x2 w[32];
; #pragma unroll
;         for (int u = 0; u < 32; ++u) w[u] = *(const f32x2*)(W + (size_t)(k + u) * NMOD6);
; #pragma unroll
;         for (int u4 = 0; u4 < 8; ++u4) {
; #pragma unroll
;           for (int r = 0; r < 9; ++r) { const f32x4 cv = *(const LAS f32x4*)(condL + r * 2048 + ks * 256 + k + 4 * u4);
; #pragma unroll
;             for (int e = 0; e < 4; ++e) { a0[r] = fmaf(cv[e], w[4 * u4 + e].x, a0[r]); a1[r] = fmaf(cv[e], w[4 * u4 + e].y, a1[r]); } }
;         }
.Lgemv_loop:
	ds_read_b128 v[24:27], v46 offset:16
	ds_read_b128 v[28:31], v46 offset:8208
	ds_read_b128 v[32:35], v46 offset:16400
	ds_read_b128 v[36:39], v46 offset:24592
	ds_read_b128 v[148:151], v46 offset:32784
	ds_read_b128 v[2:5], v46 offset:40976
	ds_read_b128 v[10:13], v46 offset:49168
	ds_read_b128 v[166:169], v46 offset:57360
	ds_read_b128 v[172:175], v89 offset:16
	s_waitcnt vmcnt(28) lgkmcnt(9)
	v_pk_fma_f32 v[122:123], v[104:105], v[182:183], v[122:123] op_sel_hi:[0,1,1]
	v_pk_fma_f32 v[120:121], v[108:109], v[182:183], v[120:121] op_sel_hi:[0,1,1]
	v_pk_fma_f32 v[40:41], v[112:113], v[182:183], v[40:41] op_sel_hi:[0,1,1]
	v_pk_fma_f32 v[22:23], v[116:117], v[182:183], v[22:23] op_sel_hi:[0,1,1]
	v_pk_fma_f32 v[20:21], v[124:125], v[182:183], v[20:21] op_sel_hi:[0,1,1]
	v_pk_fma_f32 v[8:9], v[128:129], v[182:183], v[8:9] op_sel_hi:[0,1,1]
	v_pk_fma_f32 v[16:17], v[132:133], v[182:183], v[16:17] op_sel_hi:[0,1,1]
	v_pk_fma_f32 v[18:19], v[136:137], v[182:183], v[18:19] op_sel_hi:[0,1,1]
	v_pk_fma_f32 v[6:7], v[140:141], v[182:183], v[6:7] op_sel_hi:[0,1,1]
	v_pk_fma_f32 v[122:123], v[104:105], v[184:185], v[122:123] op_sel:[1,0,0]
	v_pk_fma_f32 v[120:121], v[108:109], v[184:185], v[120:121] op_sel:[1,0,0]
	v_pk_fma_f32 v[40:41], v[112:113], v[184:185], v[40:41] op_sel:[1,0,0]
	v_pk_fma_f32 v[22:23], v[116:117], v[184:185], v[22:23] op_sel:[1,0,0]
	v_pk_fma_f32 v[20:21], v[124:125], v[184:185], v[20:21] op_sel:[1,0,0]
	v_pk_fma_f32 v[8:9], v[128:129], v[184:185], v[8:9] op_sel:[1,0,0]
	v_pk_fma_f32 v[16:17], v[132:133], v[184:185], v[16:17] op_sel:[1,0,0]
	v_pk_fma_f32 v[18:19], v[136:137], v[184:185], v[18:19] op_sel:[1,0,0]
	v_pk_fma_f32 v[6:7], v[140:141], v[184:185], v[6:7] op_sel:[1,0,0]
	v_pk_fma_f32 v[122:123], v[106:107], v[186:187], v[122:123] op_sel_hi:[0,1,1]
	v_pk_fma_f32 v[120:121], v[110:111], v[186:187], v[120:121] op_sel_hi:[0,1,1]
	v_pk_fma_f32 v[40:41], v[114:115], v[186:187], v[40:41] op_sel_hi:[0,1,1]
	v_pk_fma_f32 v[22:23], v[118:119], v[186:187], v[22:23] op_sel_hi:[0,1,1]
	v_pk_fma_f32 v[20:21], v[126:127], v[186:187], v[20:21] op_sel_hi:[0,1,1]
	v_pk_fma_f32 v[8:9], v[130:131], v[186:187], v[8:9] op_sel_hi:[0,1,1]
	v_pk_fma_f32 v[16:17], v[134:135], v[186:187], v[16:17] op_sel_hi:[0,1,1]
	v_pk_fma_f32 v[18:19], v[138:139], v[186:187], v[18:19] op_sel_hi:[0,1,1]
	v_pk_fma_f32 v[6:7], v[142:143], v[186:187], v[6:7] op_sel_hi:[0,1,1]
	v_pk_fma_f32 v[122:123], v[106:107], v[188:189], v[122:123] op_sel:[1,0,0]
	v_pk_fma_f32 v[120:121], v[110:111], v[188:189], v[120:121] op_sel:[1,0,0]
	v_pk_fma_f32 v[40:41], v[114:115], v[188:189], v[40:41] op_sel:[1,0,0]
	v_pk_fma_f32 v[22:23], v[118:119], v[188:189], v[22:23] op_sel:[1,0,0]
	v_pk_fma_f32 v[20:21], v[126:127], v[188:189], v[20:21] op_sel:[1,0,0]
	v_pk_fma_f32 v[8:9], v[130:131], v[188:189], v[8:9] op_sel:[1,0,0]
	v_pk_fma_f32 v[16:17], v[134:135], v[188:189], v[16:17] op_sel:[1,0,0]
	v_pk_fma_f32 v[18:19], v[138:139], v[188:189], v[18:19] op_sel:[1,0,0]
	v_pk_fma_f32 v[6:7], v[142:143], v[188:189], v[6:7] op_sel:[1,0,0]
	global_load_dwordx2 v[182:183], v144, s[100:101]
	s_add_u32 s100, s100, 0xc000
	s_addc_u32 s101, s101, 0
	global_load_dwordx2 v[184:185], v144, s[100:101]
	s_add_u32 s100, s100, 0xc000
	s_addc_u32 s101, s101, 0
	global_load_dwordx2 v[186:187], v144, s[100:101]
	s_add_u32 s100, s100, 0xc000
	s_addc_u32 s101, s101, 0
	global_load_dwordx2 v[188:189], v144, s[100:101]
	s_add_u32 s100, s100, 0xc000
	s_addc_u32 s101, s101, 0
	ds_read_b128 v[104:107], v46 offset:32
	ds_read_b128 v[108:111], v46 offset:8224
	ds_read_b128 v[112:115], v46 offset:16416
	ds_read_b128 v[116:119], v46 offset:24608
	ds_read_b128 v[124:127], v46 offset:32800
	ds_read_b128 v[128:131], v46 offset:40992
	ds_read_b128 v[132:135], v46 offset:49184
	ds_read_b128 v[136:139], v46 offset:57376
	ds_read_b128 v[140:143], v89 offset:32
	s_waitcnt vmcnt(28) lgkmcnt(9)
	v_pk_fma_f32 v[122:123], v[24:25], v[190:191], v[122:123] op_sel_hi:[0,1,1]
	v_pk_fma_f32 v[120:121], v[28:29], v[190:191], v[120:121] op_sel_hi:[0,1,1]
	v_pk_fma_f32 v[40:41], v[32:33], v[190:191], v[40:41] op_sel_hi:[0,1,1]
	v_pk_fma_f32 v[22:23], v[36:37], v[190:191], v[22:23] op_sel_hi:[0,1,1]
	v_pk_fma_f32 v[20:21], v[148:149], v[190:191], v[20:21] op_sel_hi:[0,1,1]
	v_pk_fma_f32 v[8:9], v[2:3], v[190:191], v[8:9] op_sel_hi:[0,1,1]
	v_pk_fma_f32 v[16:17], v[10:11], v[190:191], v[16:17] op_sel_hi:[0,1,1]
	v_pk_fma_f32 v[18:19], v[166:167], v[190:191], v[18:19] op_sel_hi:[0,1,1]
	v_pk_fma_f32 v[6:7], v[172:173], v[190:191], v[6:7] op_sel_hi:[0,1,1]
	v_pk_fma_f32 v[122:123], v[24:25], v[192:193], v[122:123] op_sel:[1,0,0]
	v_pk_fma_f32 v[120:121], v[28:29], v[192:193], v[120:121] op_sel:[1,0,0]
	v_pk_fma_f32 v[40:41], v[32:33], v[192:193], v[40:41] op_sel:[1,0,0]
	v_pk_fma_f32 v[22:23], v[36:37], v[192:193], v[22:23] op_sel:[1,0,0]
	v_pk_fma_f32 v[20:21], v[148:149], v[192:193], v[20:21] op_sel:[1,0,0]
	v_pk_fma_f32 v[8:9], v[2:3], v[192:193], v[8:9] op_sel:[1,0,0]
	v_pk_fma_f32 v[16:17], v[10:11], v[192:193], v[16:17] op_sel:[1,0,0]
	v_pk_fma_f32 v[18:19], v[166:167], v[192:193], v[18:19] op_sel:[1,0,0]
	v_pk_fma_f32 v[6:7], v[172:173], v[192:193], v[6:7] op_sel:[1,0,0]
	v_pk_fma_f32 v[122:123], v[26:27], v[194:195], v[122:123] op_sel_hi:[0,1,1]
	v_pk_fma_f32 v[120:121], v[30:31], v[194:195], v[120:121] op_sel_hi:[0,1,1]
	v_pk_fma_f32 v[40:41], v[34:35], v[194:195], v[40:41] op_sel_hi:[0,1,1]
	v_pk_fma_f32 v[22:23], v[38:39], v[194:195], v[22:23] op_sel_hi:[0,1,1]
	v_pk_fma_f32 v[20:21], v[150:151], v[194:195], v[20:21] op_sel_hi:[0,1,1]
	v_pk_fma_f32 v[8:9], v[4:5], v[194:195], v[8:9] op_sel_hi:[0,1,1]
; #define LAS __attribute__((address_space(3)))
; __device__ __forceinline__ void phase0(const Params& p, char* shm) {
;     ...
;       for (int k = 0; k < 256; k += 32) {
;         f32x2 w[32];
; #pragma unroll
;         for (int u = 0; u < 32; ++u) w[u] = *(const f32x2*)(W + (size_t)(k + u) * NMOD6);
; #pragma unroll
;         for (int u4 = 0; u4 < 8; ++u4) {
; #pragma unroll
;           for (int r = 0; r < 9; ++r) { const f32x4 cv = *(const LAS f32x4*)(condL + r * 2048 + ks * 256 + k + 4 * u4);
; #pragma unroll
;             for (int e = 0; e < 4; ++e) { a0[r] = fmaf(cv[e], w[4 * u4 + e].x, a0[r]); a1[r] = fmaf(cv[e], w[4 * u4 + e].y, a1[r]); } }
;         }
	v_pk_fma_f32 v[16:17], v[12:13], v[194:195], v[16:17] op_sel_hi:[0,1,1]
	v_pk_fma_f32 v[18:19], v[168:169], v[194:195], v[18:19] op_sel_hi:[0,1,1]
	v_pk_fma_f32 v[6:7], v[174:175], v[194:195], v[6:7] op_sel_hi:[0,1,1]
	v_pk_fma_f32 v[122:123], v[26:27], v[196:197], v[122:123] op_sel:[1,0,0]
	v_pk_fma_f32 v[120:121], v[30:31], v[196:197], v[120:121] op_sel:[1,0,0]
	v_pk_fma_f32 v[40:41], v[34:35], v[196:197], v[40:41] op_sel:[1,0,0]
	v_pk_fma_f32 v[22:23], v[38:39], v[196:197], v[22:23] op_sel:[1,0,0]
	v_pk_fma_f32 v[20:21], v[150:151], v[196:197], v[20:21] op_sel:[1,0,0]
	v_pk_fma_f32 v[8:9], v[4:5], v[196:197], v[8:9] op_sel:[1,0,0]
	v_pk_fma_f32 v[16:17], v[12:13], v[196:197], v[16:17] op_sel:[1,0,0]
	v_pk_fma_f32 v[18:19], v[168:169], v[196:197], v[18:19] op_sel:[1,0,0]
	v_pk_fma_f32 v[6:7], v[174:175], v[196:197], v[6:7] op_sel:[1,0,0]
	global_load_dwordx2 v[190:191], v144, s[100:101]
	s_add_u32 s100, s100, 0xc000
	s_addc_u32 s101, s101, 0
	global_load_dwordx2 v[192:193], v144, s[100:101]
	s_add_u32 s100, s100, 0xc000
	s_addc_u32 s101, s101, 0
	global_load_dwordx2 v[194:195], v144, s[100:101]
	s_add_u32 s100, s100, 0xc000
	s_addc_u32 s101, s101, 0
	global_load_dwordx2 v[196:197], v144, s[100:101]
	s_add_u32 s100, s100, 0xc000
	s_addc_u32 s101, s101, 0
	ds_read_b128 v[24:27], v46 offset:48
	ds_read_b128 v[28:31], v46 offset:8240
	ds_read_b128 v[32:35], v46 offset:16432
	ds_read_b128 v[36:39], v46 offset:24624
	ds_read_b128 v[148:151], v46 offset:32816
	ds_read_b128 v[2:5], v46 offset:41008
	ds_read_b128 v[10:13], v46 offset:49200
	ds_read_b128 v[166:169], v46 offset:57392
	ds_read_b128 v[172:175], v89 offset:48
	s_waitcnt vmcnt(28) lgkmcnt(9)
	v_pk_fma_f32 v[122:123], v[104:105], v[198:199], v[122:123] op_sel_hi:[0,1,1]
	v_pk_fma_f32 v[120:121], v[108:109], v[198:199], v[120:121] op_sel_hi:[0,1,1]
	v_pk_fma_f32 v[40:41], v[112:113], v[198:199], v[40:41] op_sel_hi:[0,1,1]
	v_pk_fma_f32 v[22:23], v[116:117], v[198:199], v[22:23] op_sel_hi:[0,1,1]
	v_pk_fma_f32 v[20:21], v[124:125], v[198:199], v[20:21] op_sel_hi:[0,1,1]
	v_pk_fma_f32 v[8:9], v[128:129], v[198:199], v[8:9] op_sel_hi:[0,1,1]
	v_pk_fma_f32 v[16:17], v[132:133], v[198:199], v[16:17] op_sel_hi:[0,1,1]
	v_pk_fma_f32 v[18:19], v[136:137], v[198:199], v[18:19] op_sel_hi:[0,1,1]
	v_pk_fma_f32 v[6:7], v[140:141], v[198:199], v[6:7] op_sel_hi:[0,1,1]
	v_pk_fma_f32 v[122:123], v[104:105], v[200:201], v[122:123] op_sel:[1,0,0]
	v_pk_fma_f32 v[120:121], v[108:109], v[200:201], v[120:121] op_sel:[1,0,0]
	v_pk_fma_f32 v[40:41], v[112:113], v[200:201], v[40:41] op_sel:[1,0,0]
	v_pk_fma_f32 v[22:23], v[116:117], v[200:201], v[22:23] op_sel:[1,0,0]
	v_pk_fma_f32 v[20:21], v[124:125], v[200:201], v[20:21] op_sel:[1,0,0]
	v_pk_fma_f32 v[8:9], v[128:129], v[200:201], v[8:9] op_sel:[1,0,0]
	v_pk_fma_f32 v[16:17], v[132:133], v[200:201], v[16:17] op_sel:[1,0,0]
	v_pk_fma_f32 v[18:19], v[136:137], v[200:201], v[18:19] op_sel:[1,0,0]
	v_pk_fma_f32 v[6:7], v[140:141], v[200:201], v[6:7] op_sel:[1,0,0]
	v_pk_fma_f32 v[122:123], v[106:107], v[202:203], v[122:123] op_sel_hi:[0,1,1]
	v_pk_fma_f32 v[120:121], v[110:111], v[202:203], v[120:121] op_sel_hi:[0,1,1]
	v_pk_fma_f32 v[40:41], v[114:115], v[202:203], v[40:41] op_sel_hi:[0,1,1]
	v_pk_fma_f32 v[22:23], v[118:119], v[202:203], v[22:23] op_sel_hi:[0,1,1]
	v_pk_fma_f32 v[20:21], v[126:127], v[202:203], v[20:21] op_sel_hi:[0,1,1]
	v_pk_fma_f32 v[8:9], v[130:131], v[202:203], v[8:9] op_sel_hi:[0,1,1]
	v_pk_fma_f32 v[16:17], v[134:135], v[202:203], v[16:17] op_sel_hi:[0,1,1]
	v_pk_fma_f32 v[18:19], v[138:139], v[202:203], v[18:19] op_sel_hi:[0,1,1]
	v_pk_fma_f32 v[6:7], v[142:143], v[202:203], v[6:7] op_sel_hi:[0,1,1]
	v_pk_fma_f32 v[122:123], v[106:107], v[204:205], v[122:123] op_sel:[1,0,0]
	v_pk_fma_f32 v[120:121], v[110:111], v[204:205], v[120:121] op_sel:[1,0,0]
	v_pk_fma_f32 v[40:41], v[114:115], v[204:205], v[40:41] op_sel:[1,0,0]
	v_pk_fma_f32 v[22:23], v[118:119], v[204:205], v[22:23] op_sel:[1,0,0]
	v_pk_fma_f32 v[20:21], v[126:127], v[204:205], v[20:21] op_sel:[1,0,0]
	v_pk_fma_f32 v[8:9], v[130:131], v[204:205], v[8:9] op_sel:[1,0,0]
	v_pk_fma_f32 v[16:17], v[134:135], v[204:205], v[16:17] op_sel:[1,0,0]
	v_pk_fma_f32 v[18:19], v[138:139], v[204:205], v[18:19] op_sel:[1,0,0]
	v_pk_fma_f32 v[6:7], v[142:143], v[204:205], v[6:7] op_sel:[1,0,0]
	global_load_dwordx2 v[198:199], v144, s[100:101]
	s_add_u32 s100, s100, 0xc000
	s_addc_u32 s101, s101, 0
	global_load_dwordx2 v[200:201], v144, s[100:101]
	s_add_u32 s100, s100, 0xc000
	s_addc_u32 s101, s101, 0
	global_load_dwordx2 v[202:203], v144, s[100:101]
	s_add_u32 s100, s100, 0xc000
	s_addc_u32 s101, s101, 0
	global_load_dwordx2 v[204:205], v144, s[100:101]
	s_add_u32 s100, s100, 0xc000
	s_addc_u32 s101, s101, 0
	ds_read_b128 v[104:107], v46 offset:64
	ds_read_b128 v[108:111], v46 offset:8256
	ds_read_b128 v[112:115], v46 offset:16448
	ds_read_b128 v[116:119], v46 offset:24640
	ds_read_b128 v[124:127], v46 offset:32832
	ds_read_b128 v[128:131], v46 offset:41024
	ds_read_b128 v[132:135], v46 offset:49216
	ds_read_b128 v[136:139], v46 offset:57408
	ds_read_b128 v[140:143], v89 offset:64
	s_waitcnt vmcnt(28) lgkmcnt(9)
; #define LAS __attribute__((address_space(3)))
; __device__ __forceinline__ void phase0(const Params& p, char* shm) {
;     ...
;       for (int k = 0; k < 256; k += 32) {
;         f32x2 w[32];
; #pragma unroll
;         for (int u = 0; u < 32; ++u) w[u] = *(const f32x2*)(W + (size_t)(k + u) * NMOD6);
; #pragma unroll
;         for (int u4 = 0; u4 < 8; ++u4) {
; #pragma unroll
;           for (int r = 0; r < 9; ++r) { const f32x4 cv = *(const LAS f32x4*)(condL + r * 2048 + ks * 256 + k + 4 * u4);
; #pragma unroll
;             for (int e = 0; e < 4; ++e) { a0[r] = fmaf(cv[e], w[4 * u4 + e].x, a0[r]); a1[r] = fmaf(cv[e], w[4 * u4 + e].y, a1[r]); } }
;         }
	v_pk_fma_f32 v[122:123], v[24:25], v[206:207], v[122:123] op_sel_hi:[0,1,1]
	v_pk_fma_f32 v[120:121], v[28:29], v[206:207], v[120:121] op_sel_hi:[0,1,1]
	v_pk_fma_f32 v[40:41], v[32:33], v[206:207], v[40:41] op_sel_hi:[0,1,1]
	v_pk_fma_f32 v[22:23], v[36:37], v[206:207], v[22:23] op_sel_hi:[0,1,1]
	v_pk_fma_f32 v[20:21], v[148:149], v[206:207], v[20:21] op_sel_hi:[0,1,1]
	v_pk_fma_f32 v[8:9], v[2:3], v[206:207], v[8:9] op_sel_hi:[0,1,1]
	v_pk_fma_f32 v[16:17], v[10:11], v[206:207], v[16:17] op_sel_hi:[0,1,1]
	v_pk_fma_f32 v[18:19], v[166:167], v[206:207], v[18:19] op_sel_hi:[0,1,1]
	v_pk_fma_f32 v[6:7], v[172:173], v[206:207], v[6:7] op_sel_hi:[0,1,1]
	v_pk_fma_f32 v[122:123], v[24:25], v[208:209], v[122:123] op_sel:[1,0,0]
	v_pk_fma_f32 v[120:121], v[28:29], v[208:209], v[120:121] op_sel:[1,0,0]
	v_pk_fma_f32 v[40:41], v[32:33], v[208:209], v[40:41] op_sel:[1,0,0]
	v_pk_fma_f32 v[22:23], v[36:37], v[208:209], v[22:23] op_sel:[1,0,0]
	v_pk_fma_f32 v[20:21], v[148:149], v[208:209], v[20:21] op_sel:[1,0,0]
	v_pk_fma_f32 v[8:9], v[2:3], v[208:209], v[8:9] op_sel:[1,0,0]
	v_pk_fma_f32 v[16:17], v[10:11], v[208:209], v[16:17] op_sel:[1,0,0]
	v_pk_fma_f32 v[18:19], v[166:167], v[208:209], v[18:19] op_sel:[1,0,0]
	v_pk_fma_f32 v[6:7], v[172:173], v[208:209], v[6:7] op_sel:[1,0,0]
	v_pk_fma_f32 v[122:123], v[26:27], v[210:211], v[122:123] op_sel_hi:[0,1,1]
	v_pk_fma_f32 v[120:121], v[30:31], v[210:211], v[120:121] op_sel_hi:[0,1,1]
	v_pk_fma_f32 v[40:41], v[34:35], v[210:211], v[40:41] op_sel_hi:[0,1,1]
	v_pk_fma_f32 v[22:23], v[38:39], v[210:211], v[22:23] op_sel_hi:[0,1,1]
	v_pk_fma_f32 v[20:21], v[150:151], v[210:211], v[20:21] op_sel_hi:[0,1,1]
	v_pk_fma_f32 v[8:9], v[4:5], v[210:211], v[8:9] op_sel_hi:[0,1,1]
	v_pk_fma_f32 v[16:17], v[12:13], v[210:211], v[16:17] op_sel_hi:[0,1,1]
	v_pk_fma_f32 v[18:19], v[168:169], v[210:211], v[18:19] op_sel_hi:[0,1,1]
	v_pk_fma_f32 v[6:7], v[174:175], v[210:211], v[6:7] op_sel_hi:[0,1,1]
	v_pk_fma_f32 v[122:123], v[26:27], v[212:213], v[122:123] op_sel:[1,0,0]
	v_pk_fma_f32 v[120:121], v[30:31], v[212:213], v[120:121] op_sel:[1,0,0]
	v_pk_fma_f32 v[40:41], v[34:35], v[212:213], v[40:41] op_sel:[1,0,0]
	v_pk_fma_f32 v[22:23], v[38:39], v[212:213], v[22:23] op_sel:[1,0,0]
	v_pk_fma_f32 v[20:21], v[150:151], v[212:213], v[20:21] op_sel:[1,0,0]
	v_pk_fma_f32 v[8:9], v[4:5], v[212:213], v[8:9] op_sel:[1,0,0]
	v_pk_fma_f32 v[16:17], v[12:13], v[212:213], v[16:17] op_sel:[1,0,0]
	v_pk_fma_f32 v[18:19], v[168:169], v[212:213], v[18:19] op_sel:[1,0,0]
	v_pk_fma_f32 v[6:7], v[174:175], v[212:213], v[6:7] op_sel:[1,0,0]
	global_load_dwordx2 v[206:207], v144, s[100:101]
	s_add_u32 s100, s100, 0xc000
	s_addc_u32 s101, s101, 0
	global_load_dwordx2 v[208:209], v144, s[100:101]
	s_add_u32 s100, s100, 0xc000
	s_addc_u32 s101, s101, 0
	global_load_dwordx2 v[210:211], v144, s[100:101]
	s_add_u32 s100, s100, 0xc000
	s_addc_u32 s101, s101, 0
	global_load_dwordx2 v[212:213], v144, s[100:101]
	s_add_u32 s100, s100, 0xc000
	s_addc_u32 s101, s101, 0
	ds_read_b128 v[24:27], v46 offset:80
	ds_read_b128 v[28:31], v46 offset:8272
	ds_read_b128 v[32:35], v46 offset:16464
	ds_read_b128 v[36:39], v46 offset:24656
	ds_read_b128 v[148:151], v46 offset:32848
	ds_read_b128 v[2:5], v46 offset:41040
	ds_read_b128 v[10:13], v46 offset:49232
	ds_read_b128 v[166:169], v46 offset:57424
	ds_read_b128 v[172:175], v89 offset:80
	s_waitcnt vmcnt(28) lgkmcnt(9)
	v_pk_fma_f32 v[122:123], v[104:105], v[214:215], v[122:123] op_sel_hi:[0,1,1]
	v_pk_fma_f32 v[120:121], v[108:109], v[214:215], v[120:121] op_sel_hi:[0,1,1]
	v_pk_fma_f32 v[40:41], v[112:113], v[214:215], v[40:41] op_sel_hi:[0,1,1]
	v_pk_fma_f32 v[22:23], v[116:117], v[214:215], v[22:23] op_sel_hi:[0,1,1]
	v_pk_fma_f32 v[20:21], v[124:125], v[214:215], v[20:21] op_sel_hi:[0,1,1]
	v_pk_fma_f32 v[8:9], v[128:129], v[214:215], v[8:9] op_sel_hi:[0,1,1]
	v_pk_fma_f32 v[16:17], v[132:133], v[214:215], v[16:17] op_sel_hi:[0,1,1]
	v_pk_fma_f32 v[18:19], v[136:137], v[214:215], v[18:19] op_sel_hi:[0,1,1]
	v_pk_fma_f32 v[6:7], v[140:141], v[214:215], v[6:7] op_sel_hi:[0,1,1]
	v_pk_fma_f32 v[122:123], v[104:105], v[216:217], v[122:123] op_sel:[1,0,0]
	v_pk_fma_f32 v[120:121], v[108:109], v[216:217], v[120:121] op_sel:[1,0,0]
	v_pk_fma_f32 v[40:41], v[112:113], v[216:217], v[40:41] op_sel:[1,0,0]
	v_pk_fma_f32 v[22:23], v[116:117], v[216:217], v[22:23] op_sel:[1,0,0]
	v_pk_fma_f32 v[20:21], v[124:125], v[216:217], v[20:21] op_sel:[1,0,0]
	v_pk_fma_f32 v[8:9], v[128:129], v[216:217], v[8:9] op_sel:[1,0,0]
	v_pk_fma_f32 v[16:17], v[132:133], v[216:217], v[16:17] op_sel:[1,0,0]
	v_pk_fma_f32 v[18:19], v[136:137], v[216:217], v[18:19] op_sel:[1,0,0]
	v_pk_fma_f32 v[6:7], v[140:141], v[216:217], v[6:7] op_sel:[1,0,0]
	v_pk_fma_f32 v[122:123], v[106:107], v[218:219], v[122:123] op_sel_hi:[0,1,1]
	v_pk_fma_f32 v[120:121], v[110:111], v[218:219], v[120:121] op_sel_hi:[0,1,1]
	v_pk_fma_f32 v[40:41], v[114:115], v[218:219], v[40:41] op_sel_hi:[0,1,1]
	v_pk_fma_f32 v[22:23], v[118:119], v[218:219], v[22:23] op_sel_hi:[0,1,1]
	v_pk_fma_f32 v[20:21], v[126:127], v[218:219], v[20:21] op_sel_hi:[0,1,1]
	v_pk_fma_f32 v[8:9], v[130:131], v[218:219], v[8:9] op_sel_hi:[0,1,1]
	v_pk_fma_f32 v[16:17], v[134:135], v[218:219], v[16:17] op_sel_hi:[0,1,1]
	v_pk_fma_f32 v[18:19], v[138:139], v[218:219], v[18:19] op_sel_hi:[0,1,1]
	v_pk_fma_f32 v[6:7], v[142:143], v[218:219], v[6:7] op_sel_hi:[0,1,1]
	v_pk_fma_f32 v[122:123], v[106:107], v[220:221], v[122:123] op_sel:[1,0,0]
	v_pk_fma_f32 v[120:121], v[110:111], v[220:221], v[120:121] op_sel:[1,0,0]
	v_pk_fma_f32 v[40:41], v[114:115], v[220:221], v[40:41] op_sel:[1,0,0]
	v_pk_fma_f32 v[22:23], v[118:119], v[220:221], v[22:23] op_sel:[1,0,0]
	v_pk_fma_f32 v[20:21], v[126:127], v[220:221], v[20:21] op_sel:[1,0,0]
	v_pk_fma_f32 v[8:9], v[130:131], v[220:221], v[8:9] op_sel:[1,0,0]
	v_pk_fma_f32 v[16:17], v[134:135], v[220:221], v[16:17] op_sel:[1,0,0]
	v_pk_fma_f32 v[18:19], v[138:139], v[220:221], v[18:19] op_sel:[1,0,0]
	v_pk_fma_f32 v[6:7], v[142:143], v[220:221], v[6:7] op_sel:[1,0,0]
	global_load_dwordx2 v[214:215], v144, s[100:101]
	s_add_u32 s100, s100, 0xc000
	s_addc_u32 s101, s101, 0
	global_load_dwordx2 v[216:217], v144, s[100:101]
	s_add_u32 s100, s100, 0xc000
	s_addc_u32 s101, s101, 0
	global_load_dwordx2 v[218:219], v144, s[100:101]
	s_add_u32 s100, s100, 0xc000
	s_addc_u32 s101, s101, 0
	global_load_dwordx2 v[220:221], v144, s[100:101]
	s_add_u32 s100, s100, 0xc000
	s_addc_u32 s101, s101, 0
	ds_read_b128 v[104:107], v46 offset:96
	ds_read_b128 v[108:111], v46 offset:8288
	ds_read_b128 v[112:115], v46 offset:16480
	ds_read_b128 v[116:119], v46 offset:24672
	ds_read_b128 v[124:127], v46 offset:32864
	ds_read_b128 v[128:131], v46 offset:41056
	ds_read_b128 v[132:135], v46 offset:49248
	ds_read_b128 v[136:139], v46 offset:57440
	ds_read_b128 v[140:143], v89 offset:96
	s_waitcnt vmcnt(28) lgkmcnt(9)
; #define LAS __attribute__((address_space(3)))
; __device__ __forceinline__ void phase0(const Params& p, char* shm) {
;     ...
;       for (int k = 0; k < 256; k += 32) {
;         f32x2 w[32];
; #pragma unroll
;         for (int u = 0; u < 32; ++u) w[u] = *(const f32x2*)(W + (size_t)(k + u) * NMOD6);
; #pragma unroll
;         for (int u4 = 0; u4 < 8; ++u4) {
; #pragma unroll
;           for (int r = 0; r < 9; ++r) { const f32x4 cv = *(const LAS f32x4*)(condL + r * 2048 + ks * 256 + k + 4 * u4);
; #pragma unroll
;             for (int e = 0; e < 4; ++e) { a0[r] = fmaf(cv[e], w[4 * u4 + e].x, a0[r]); a1[r] = fmaf(cv[e], w[4 * u4 + e].y, a1[r]); } }
;         }
	v_pk_fma_f32 v[122:123], v[24:25], v[222:223], v[122:123] op_sel_hi:[0,1,1]
	v_pk_fma_f32 v[120:121], v[28:29], v[222:223], v[120:121] op_sel_hi:[0,1,1]
	v_pk_fma_f32 v[40:41], v[32:33], v[222:223], v[40:41] op_sel_hi:[0,1,1]
	v_pk_fma_f32 v[22:23], v[36:37], v[222:223], v[22:23] op_sel_hi:[0,1,1]
	v_pk_fma_f32 v[20:21], v[148:149], v[222:223], v[20:21] op_sel_hi:[0,1,1]
	v_pk_fma_f32 v[8:9], v[2:3], v[222:223], v[8:9] op_sel_hi:[0,1,1]
	v_pk_fma_f32 v[16:17], v[10:11], v[222:223], v[16:17] op_sel_hi:[0,1,1]
	v_pk_fma_f32 v[18:19], v[166:167], v[222:223], v[18:19] op_sel_hi:[0,1,1]
	v_pk_fma_f32 v[6:7], v[172:173], v[222:223], v[6:7] op_sel_hi:[0,1,1]
	v_pk_fma_f32 v[122:123], v[24:25], v[224:225], v[122:123] op_sel:[1,0,0]
	v_pk_fma_f32 v[120:121], v[28:29], v[224:225], v[120:121] op_sel:[1,0,0]
	v_pk_fma_f32 v[40:41], v[32:33], v[224:225], v[40:41] op_sel:[1,0,0]
	v_pk_fma_f32 v[22:23], v[36:37], v[224:225], v[22:23] op_sel:[1,0,0]
	v_pk_fma_f32 v[20:21], v[148:149], v[224:225], v[20:21] op_sel:[1,0,0]
	v_pk_fma_f32 v[8:9], v[2:3], v[224:225], v[8:9] op_sel:[1,0,0]
	v_pk_fma_f32 v[16:17], v[10:11], v[224:225], v[16:17] op_sel:[1,0,0]
	v_pk_fma_f32 v[18:19], v[166:167], v[224:225], v[18:19] op_sel:[1,0,0]
	v_pk_fma_f32 v[6:7], v[172:173], v[224:225], v[6:7] op_sel:[1,0,0]
	v_pk_fma_f32 v[122:123], v[26:27], v[226:227], v[122:123] op_sel_hi:[0,1,1]
	v_pk_fma_f32 v[120:121], v[30:31], v[226:227], v[120:121] op_sel_hi:[0,1,1]
	v_pk_fma_f32 v[40:41], v[34:35], v[226:227], v[40:41] op_sel_hi:[0,1,1]
	v_pk_fma_f32 v[22:23], v[38:39], v[226:227], v[22:23] op_sel_hi:[0,1,1]
	v_pk_fma_f32 v[20:21], v[150:151], v[226:227], v[20:21] op_sel_hi:[0,1,1]
	v_pk_fma_f32 v[8:9], v[4:5], v[226:227], v[8:9] op_sel_hi:[0,1,1]
	v_pk_fma_f32 v[16:17], v[12:13], v[226:227], v[16:17] op_sel_hi:[0,1,1]
	v_pk_fma_f32 v[18:19], v[168:169], v[226:227], v[18:19] op_sel_hi:[0,1,1]
	v_pk_fma_f32 v[6:7], v[174:175], v[226:227], v[6:7] op_sel_hi:[0,1,1]
	v_pk_fma_f32 v[122:123], v[26:27], v[228:229], v[122:123] op_sel:[1,0,0]
	v_pk_fma_f32 v[120:121], v[30:31], v[228:229], v[120:121] op_sel:[1,0,0]
	v_pk_fma_f32 v[40:41], v[34:35], v[228:229], v[40:41] op_sel:[1,0,0]
	v_pk_fma_f32 v[22:23], v[38:39], v[228:229], v[22:23] op_sel:[1,0,0]
	v_pk_fma_f32 v[20:21], v[150:151], v[228:229], v[20:21] op_sel:[1,0,0]
	v_pk_fma_f32 v[8:9], v[4:5], v[228:229], v[8:9] op_sel:[1,0,0]
	v_pk_fma_f32 v[16:17], v[12:13], v[228:229], v[16:17] op_sel:[1,0,0]
	v_pk_fma_f32 v[18:19], v[168:169], v[228:229], v[18:19] op_sel:[1,0,0]
	v_pk_fma_f32 v[6:7], v[174:175], v[228:229], v[6:7] op_sel:[1,0,0]
	global_load_dwordx2 v[222:223], v144, s[100:101]
	s_add_u32 s100, s100, 0xc000
	s_addc_u32 s101, s101, 0
	global_load_dwordx2 v[224:225], v144, s[100:101]
	s_add_u32 s100, s100, 0xc000
	s_addc_u32 s101, s101, 0
	global_load_dwordx2 v[226:227], v144, s[100:101]
	s_add_u32 s100, s100, 0xc000
	s_addc_u32 s101, s101, 0
	global_load_dwordx2 v[228:229], v144, s[100:101]
	s_add_u32 s100, s100, 0xc000
	s_addc_u32 s101, s101, 0
	ds_read_b128 v[24:27], v46 offset:112
	ds_read_b128 v[28:31], v46 offset:8304
	ds_read_b128 v[32:35], v46 offset:16496
	ds_read_b128 v[36:39], v46 offset:24688
	ds_read_b128 v[148:151], v46 offset:32880
	ds_read_b128 v[2:5], v46 offset:41072
	ds_read_b128 v[10:13], v46 offset:49264
	ds_read_b128 v[166:169], v46 offset:57456
	ds_read_b128 v[172:175], v89 offset:112
	s_waitcnt vmcnt(28) lgkmcnt(9)
	v_pk_fma_f32 v[122:123], v[104:105], v[230:231], v[122:123] op_sel_hi:[0,1,1]
	v_pk_fma_f32 v[120:121], v[108:109], v[230:231], v[120:121] op_sel_hi:[0,1,1]
	v_pk_fma_f32 v[40:41], v[112:113], v[230:231], v[40:41] op_sel_hi:[0,1,1]
	v_pk_fma_f32 v[22:23], v[116:117], v[230:231], v[22:23] op_sel_hi:[0,1,1]
	v_pk_fma_f32 v[20:21], v[124:125], v[230:231], v[20:21] op_sel_hi:[0,1,1]
	v_pk_fma_f32 v[8:9], v[128:129], v[230:231], v[8:9] op_sel_hi:[0,1,1]
	v_pk_fma_f32 v[16:17], v[132:133], v[230:231], v[16:17] op_sel_hi:[0,1,1]
	v_pk_fma_f32 v[18:19], v[136:137], v[230:231], v[18:19] op_sel_hi:[0,1,1]
	v_pk_fma_f32 v[6:7], v[140:141], v[230:231], v[6:7] op_sel_hi:[0,1,1]
	v_pk_fma_f32 v[122:123], v[104:105], v[232:233], v[122:123] op_sel:[1,0,0]
	v_pk_fma_f32 v[120:121], v[108:109], v[232:233], v[120:121] op_sel:[1,0,0]
	v_pk_fma_f32 v[40:41], v[112:113], v[232:233], v[40:41] op_sel:[1,0,0]
	v_pk_fma_f32 v[22:23], v[116:117], v[232:233], v[22:23] op_sel:[1,0,0]
	v_pk_fma_f32 v[20:21], v[124:125], v[232:233], v[20:21] op_sel:[1,0,0]
	v_pk_fma_f32 v[8:9], v[128:129], v[232:233], v[8:9] op_sel:[1,0,0]
	v_pk_fma_f32 v[16:17], v[132:133], v[232:233], v[16:17] op_sel:[1,0,0]
	v_pk_fma_f32 v[18:19], v[136:137], v[232:233], v[18:19] op_sel:[1,0,0]
	v_pk_fma_f32 v[6:7], v[140:141], v[232:233], v[6:7] op_sel:[1,0,0]
	v_pk_fma_f32 v[122:123], v[106:107], v[234:235], v[122:123] op_sel_hi:[0,1,1]
	v_pk_fma_f32 v[120:121], v[110:111], v[234:235], v[120:121] op_sel_hi:[0,1,1]
	v_pk_fma_f32 v[40:41], v[114:115], v[234:235], v[40:41] op_sel_hi:[0,1,1]
	v_pk_fma_f32 v[22:23], v[118:119], v[234:235], v[22:23] op_sel_hi:[0,1,1]
	v_pk_fma_f32 v[20:21], v[126:127], v[234:235], v[20:21] op_sel_hi:[0,1,1]
	v_pk_fma_f32 v[8:9], v[130:131], v[234:235], v[8:9] op_sel_hi:[0,1,1]
	v_pk_fma_f32 v[16:17], v[134:135], v[234:235], v[16:17] op_sel_hi:[0,1,1]
	v_pk_fma_f32 v[18:19], v[138:139], v[234:235], v[18:19] op_sel_hi:[0,1,1]
	v_pk_fma_f32 v[6:7], v[142:143], v[234:235], v[6:7] op_sel_hi:[0,1,1]
	v_pk_fma_f32 v[122:123], v[106:107], v[236:237], v[122:123] op_sel:[1,0,0]
	v_pk_fma_f32 v[120:121], v[110:111], v[236:237], v[120:121] op_sel:[1,0,0]
	v_pk_fma_f32 v[40:41], v[114:115], v[236:237], v[40:41] op_sel:[1,0,0]
	v_pk_fma_f32 v[22:23], v[118:119], v[236:237], v[22:23] op_sel:[1,0,0]
	v_pk_fma_f32 v[20:21], v[126:127], v[236:237], v[20:21] op_sel:[1,0,0]
	v_pk_fma_f32 v[8:9], v[130:131], v[236:237], v[8:9] op_sel:[1,0,0]
	v_pk_fma_f32 v[16:17], v[134:135], v[236:237], v[16:17] op_sel:[1,0,0]
	v_pk_fma_f32 v[18:19], v[138:139], v[236:237], v[18:19] op_sel:[1,0,0]
	v_pk_fma_f32 v[6:7], v[142:143], v[236:237], v[6:7] op_sel:[1,0,0]
	global_load_dwordx2 v[230:231], v144, s[100:101]
	s_add_u32 s100, s100, 0xc000
	s_addc_u32 s101, s101, 0
	global_load_dwordx2 v[232:233], v144, s[100:101]
	s_add_u32 s100, s100, 0xc000
	s_addc_u32 s101, s101, 0
	global_load_dwordx2 v[234:235], v144, s[100:101]
	s_add_u32 s100, s100, 0xc000
	s_addc_u32 s101, s101, 0
	global_load_dwordx2 v[236:237], v144, s[100:101]
	s_add_u32 s100, s100, 0xc000
	s_addc_u32 s101, s101, 0
	v_add_u32_e32 v89, 0x80, v89
	v_add_u32_e32 v46, 0xffff0000, v89
	ds_read_b128 v[104:107], v46
	ds_read_b128 v[108:111], v46 offset:8192
	ds_read_b128 v[112:115], v46 offset:16384
	ds_read_b128 v[116:119], v46 offset:24576
	ds_read_b128 v[124:127], v46 offset:32768
	ds_read_b128 v[128:131], v46 offset:40960
	ds_read_b128 v[132:135], v46 offset:49152
	ds_read_b128 v[136:139], v46 offset:57344
	ds_read_b128 v[140:143], v89
	s_waitcnt vmcnt(28) lgkmcnt(9)
; #define LAS __attribute__((address_space(3)))
; __device__ __forceinline__ void phase0(const Params& p, char* shm) {
;     ...
;       for (int k = 0; k < 256; k += 32) {
;         f32x2 w[32];
; #pragma unroll
;         for (int u = 0; u < 32; ++u) w[u] = *(const f32x2*)(W + (size_t)(k + u) * NMOD6);
; #pragma unroll
;         for (int u4 = 0; u4 < 8; ++u4) {
; #pragma unroll
;           for (int r = 0; r < 9; ++r) { const f32x4 cv = *(const LAS f32x4*)(condL + r * 2048 + ks * 256 + k + 4 * u4);
; #pragma unroll
;             for (int e = 0; e < 4; ++e) { a0[r] = fmaf(cv[e], w[4 * u4 + e].x, a0[r]); a1[r] = fmaf(cv[e], w[4 * u4 + e].y, a1[r]); } }
;         }
	v_pk_fma_f32 v[122:123], v[24:25], v[238:239], v[122:123] op_sel_hi:[0,1,1]
	v_pk_fma_f32 v[120:121], v[28:29], v[238:239], v[120:121] op_sel_hi:[0,1,1]
	v_pk_fma_f32 v[40:41], v[32:33], v[238:239], v[40:41] op_sel_hi:[0,1,1]
	v_pk_fma_f32 v[22:23], v[36:37], v[238:239], v[22:23] op_sel_hi:[0,1,1]
	v_pk_fma_f32 v[20:21], v[148:149], v[238:239], v[20:21] op_sel_hi:[0,1,1]
	v_pk_fma_f32 v[8:9], v[2:3], v[238:239], v[8:9] op_sel_hi:[0,1,1]
	v_pk_fma_f32 v[16:17], v[10:11], v[238:239], v[16:17] op_sel_hi:[0,1,1]
	v_pk_fma_f32 v[18:19], v[166:167], v[238:239], v[18:19] op_sel_hi:[0,1,1]
	v_pk_fma_f32 v[6:7], v[172:173], v[238:239], v[6:7] op_sel_hi:[0,1,1]
	v_pk_fma_f32 v[122:123], v[24:25], v[240:241], v[122:123] op_sel:[1,0,0]
	v_pk_fma_f32 v[120:121], v[28:29], v[240:241], v[120:121] op_sel:[1,0,0]
	v_pk_fma_f32 v[40:41], v[32:33], v[240:241], v[40:41] op_sel:[1,0,0]
	v_pk_fma_f32 v[22:23], v[36:37], v[240:241], v[22:23] op_sel:[1,0,0]
	v_pk_fma_f32 v[20:21], v[148:149], v[240:241], v[20:21] op_sel:[1,0,0]
	v_pk_fma_f32 v[8:9], v[2:3], v[240:241], v[8:9] op_sel:[1,0,0]
	v_pk_fma_f32 v[16:17], v[10:11], v[240:241], v[16:17] op_sel:[1,0,0]
	v_pk_fma_f32 v[18:19], v[166:167], v[240:241], v[18:19] op_sel:[1,0,0]
	v_pk_fma_f32 v[6:7], v[172:173], v[240:241], v[6:7] op_sel:[1,0,0]
	v_pk_fma_f32 v[122:123], v[26:27], v[242:243], v[122:123] op_sel_hi:[0,1,1]
	v_pk_fma_f32 v[120:121], v[30:31], v[242:243], v[120:121] op_sel_hi:[0,1,1]
	v_pk_fma_f32 v[40:41], v[34:35], v[242:243], v[40:41] op_sel_hi:[0,1,1]
	v_pk_fma_f32 v[22:23], v[38:39], v[242:243], v[22:23] op_sel_hi:[0,1,1]
	v_pk_fma_f32 v[20:21], v[150:151], v[242:243], v[20:21] op_sel_hi:[0,1,1]
	v_pk_fma_f32 v[8:9], v[4:5], v[242:243], v[8:9] op_sel_hi:[0,1,1]
	v_pk_fma_f32 v[16:17], v[12:13], v[242:243], v[16:17] op_sel_hi:[0,1,1]
	v_pk_fma_f32 v[18:19], v[168:169], v[242:243], v[18:19] op_sel_hi:[0,1,1]
	v_pk_fma_f32 v[6:7], v[174:175], v[242:243], v[6:7] op_sel_hi:[0,1,1]
	v_pk_fma_f32 v[122:123], v[26:27], v[244:245], v[122:123] op_sel:[1,0,0]
	v_pk_fma_f32 v[120:121], v[30:31], v[244:245], v[120:121] op_sel:[1,0,0]
	v_pk_fma_f32 v[40:41], v[34:35], v[244:245], v[40:41] op_sel:[1,0,0]
	v_pk_fma_f32 v[22:23], v[38:39], v[244:245], v[22:23] op_sel:[1,0,0]
	v_pk_fma_f32 v[20:21], v[150:151], v[244:245], v[20:21] op_sel:[1,0,0]
	v_pk_fma_f32 v[8:9], v[4:5], v[244:245], v[8:9] op_sel:[1,0,0]
	v_pk_fma_f32 v[16:17], v[12:13], v[244:245], v[16:17] op_sel:[1,0,0]
	v_pk_fma_f32 v[18:19], v[168:169], v[244:245], v[18:19] op_sel:[1,0,0]
	v_pk_fma_f32 v[6:7], v[174:175], v[244:245], v[6:7] op_sel:[1,0,0]
	global_load_dwordx2 v[238:239], v144, s[100:101]
	s_add_u32 s100, s100, 0xc000
	s_addc_u32 s101, s101, 0
	global_load_dwordx2 v[240:241], v144, s[100:101]
	s_add_u32 s100, s100, 0xc000
	s_addc_u32 s101, s101, 0
	global_load_dwordx2 v[242:243], v144, s[100:101]
	s_add_u32 s100, s100, 0xc000
	s_addc_u32 s101, s101, 0
	global_load_dwordx2 v[244:245], v144, s[100:101]
	s_add_u32 s100, s100, 0xc000
	s_addc_u32 s101, s101, 0
	s_add_i32 s0, s0, 1
	s_cmp_lt_u32 s0, 7
	s_cbranch_scc1 .Lgemv_loop
	ds_read_b128 v[24:27], v46 offset:16
	ds_read_b128 v[28:31], v46 offset:8208
	ds_read_b128 v[32:35], v46 offset:16400
	ds_read_b128 v[36:39], v46 offset:24592
	ds_read_b128 v[148:151], v46 offset:32784
	ds_read_b128 v[2:5], v46 offset:40976
	ds_read_b128 v[10:13], v46 offset:49168
	ds_read_b128 v[166:169], v46 offset:57360
	ds_read_b128 v[172:175], v89 offset:16
	s_waitcnt vmcnt(28) lgkmcnt(9)
	v_pk_fma_f32 v[122:123], v[104:105], v[182:183], v[122:123] op_sel_hi:[0,1,1]
	v_pk_fma_f32 v[120:121], v[108:109], v[182:183], v[120:121] op_sel_hi:[0,1,1]
	v_pk_fma_f32 v[40:41], v[112:113], v[182:183], v[40:41] op_sel_hi:[0,1,1]
	v_pk_fma_f32 v[22:23], v[116:117], v[182:183], v[22:23] op_sel_hi:[0,1,1]
	v_pk_fma_f32 v[20:21], v[124:125], v[182:183], v[20:21] op_sel_hi:[0,1,1]
	v_pk_fma_f32 v[8:9], v[128:129], v[182:183], v[8:9] op_sel_hi:[0,1,1]
	v_pk_fma_f32 v[16:17], v[132:133], v[182:183], v[16:17] op_sel_hi:[0,1,1]
	v_pk_fma_f32 v[18:19], v[136:137], v[182:183], v[18:19] op_sel_hi:[0,1,1]
	v_pk_fma_f32 v[6:7], v[140:141], v[182:183], v[6:7] op_sel_hi:[0,1,1]
	v_pk_fma_f32 v[122:123], v[104:105], v[184:185], v[122:123] op_sel:[1,0,0]
	v_pk_fma_f32 v[120:121], v[108:109], v[184:185], v[120:121] op_sel:[1,0,0]
	v_pk_fma_f32 v[40:41], v[112:113], v[184:185], v[40:41] op_sel:[1,0,0]
	v_pk_fma_f32 v[22:23], v[116:117], v[184:185], v[22:23] op_sel:[1,0,0]
	v_pk_fma_f32 v[20:21], v[124:125], v[184:185], v[20:21] op_sel:[1,0,0]
	v_pk_fma_f32 v[8:9], v[128:129], v[184:185], v[8:9] op_sel:[1,0,0]
	v_pk_fma_f32 v[16:17], v[132:133], v[184:185], v[16:17] op_sel:[1,0,0]
	v_pk_fma_f32 v[18:19], v[136:137], v[184:185], v[18:19] op_sel:[1,0,0]
	v_pk_fma_f32 v[6:7], v[140:141], v[184:185], v[6:7] op_sel:[1,0,0]
	v_pk_fma_f32 v[122:123], v[106:107], v[186:187], v[122:123] op_sel_hi:[0,1,1]
	v_pk_fma_f32 v[120:121], v[110:111], v[186:187], v[120:121] op_sel_hi:[0,1,1]
	v_pk_fma_f32 v[40:41], v[114:115], v[186:187], v[40:41] op_sel_hi:[0,1,1]
	v_pk_fma_f32 v[22:23], v[118:119], v[186:187], v[22:23] op_sel_hi:[0,1,1]
	v_pk_fma_f32 v[20:21], v[126:127], v[186:187], v[20:21] op_sel_hi:[0,1,1]
	v_pk_fma_f32 v[8:9], v[130:131], v[186:187], v[8:9] op_sel_hi:[0,1,1]
	v_pk_fma_f32 v[16:17], v[134:135], v[186:187], v[16:17] op_sel_hi:[0,1,1]
	v_pk_fma_f32 v[18:19], v[138:139], v[186:187], v[18:19] op_sel_hi:[0,1,1]
	v_pk_fma_f32 v[6:7], v[142:143], v[186:187], v[6:7] op_sel_hi:[0,1,1]
	v_pk_fma_f32 v[122:123], v[106:107], v[188:189], v[122:123] op_sel:[1,0,0]
	v_pk_fma_f32 v[120:121], v[110:111], v[188:189], v[120:121] op_sel:[1,0,0]
	v_pk_fma_f32 v[40:41], v[114:115], v[188:189], v[40:41] op_sel:[1,0,0]
	v_pk_fma_f32 v[22:23], v[118:119], v[188:189], v[22:23] op_sel:[1,0,0]
	v_pk_fma_f32 v[20:21], v[126:127], v[188:189], v[20:21] op_sel:[1,0,0]
	v_pk_fma_f32 v[8:9], v[130:131], v[188:189], v[8:9] op_sel:[1,0,0]
	v_pk_fma_f32 v[16:17], v[134:135], v[188:189], v[16:17] op_sel:[1,0,0]
	v_pk_fma_f32 v[18:19], v[138:139], v[188:189], v[18:19] op_sel:[1,0,0]
	v_pk_fma_f32 v[6:7], v[142:143], v[188:189], v[6:7] op_sel:[1,0,0]
	ds_read_b128 v[104:107], v46 offset:32
	ds_read_b128 v[108:111], v46 offset:8224
	ds_read_b128 v[112:115], v46 offset:16416
	ds_read_b128 v[116:119], v46 offset:24608
	ds_read_b128 v[124:127], v46 offset:32800
	ds_read_b128 v[128:131], v46 offset:40992
	ds_read_b128 v[132:135], v46 offset:49184
	ds_read_b128 v[136:139], v46 offset:57376
	ds_read_b128 v[140:143], v89 offset:32
	s_waitcnt vmcnt(24) lgkmcnt(9)
; #define LAS __attribute__((address_space(3)))
; __device__ __forceinline__ void phase0(const Params& p, char* shm) {
;     ...
;       for (int k = 0; k < 256; k += 32) {
;         f32x2 w[32];
; #pragma unroll
;         for (int u = 0; u < 32; ++u) w[u] = *(const f32x2*)(W + (size_t)(k + u) * NMOD6);
; #pragma unroll
;         for (int u4 = 0; u4 < 8; ++u4) {
; #pragma unroll
;           for (int r = 0; r < 9; ++r) { const f32x4 cv = *(const LAS f32x4*)(condL + r * 2048 + ks * 256 + k + 4 * u4);
; #pragma unroll
;             for (int e = 0; e < 4; ++e) { a0[r] = fmaf(cv[e], w[4 * u4 + e].x, a0[r]); a1[r] = fmaf(cv[e], w[4 * u4 + e].y, a1[r]); } }
;         }
;       }
	v_pk_fma_f32 v[122:123], v[24:25], v[190:191], v[122:123] op_sel_hi:[0,1,1]
	v_pk_fma_f32 v[120:121], v[28:29], v[190:191], v[120:121] op_sel_hi:[0,1,1]
	v_pk_fma_f32 v[40:41], v[32:33], v[190:191], v[40:41] op_sel_hi:[0,1,1]
	v_pk_fma_f32 v[22:23], v[36:37], v[190:191], v[22:23] op_sel_hi:[0,1,1]
	v_pk_fma_f32 v[20:21], v[148:149], v[190:191], v[20:21] op_sel_hi:[0,1,1]
	v_pk_fma_f32 v[8:9], v[2:3], v[190:191], v[8:9] op_sel_hi:[0,1,1]
	v_pk_fma_f32 v[16:17], v[10:11], v[190:191], v[16:17] op_sel_hi:[0,1,1]
	v_pk_fma_f32 v[18:19], v[166:167], v[190:191], v[18:19] op_sel_hi:[0,1,1]
	v_pk_fma_f32 v[6:7], v[172:173], v[190:191], v[6:7] op_sel_hi:[0,1,1]
	v_pk_fma_f32 v[122:123], v[24:25], v[192:193], v[122:123] op_sel:[1,0,0]
	v_pk_fma_f32 v[120:121], v[28:29], v[192:193], v[120:121] op_sel:[1,0,0]
	v_pk_fma_f32 v[40:41], v[32:33], v[192:193], v[40:41] op_sel:[1,0,0]
	v_pk_fma_f32 v[22:23], v[36:37], v[192:193], v[22:23] op_sel:[1,0,0]
	v_pk_fma_f32 v[20:21], v[148:149], v[192:193], v[20:21] op_sel:[1,0,0]
	v_pk_fma_f32 v[8:9], v[2:3], v[192:193], v[8:9] op_sel:[1,0,0]
	v_pk_fma_f32 v[16:17], v[10:11], v[192:193], v[16:17] op_sel:[1,0,0]
	v_pk_fma_f32 v[18:19], v[166:167], v[192:193], v[18:19] op_sel:[1,0,0]
	v_pk_fma_f32 v[6:7], v[172:173], v[192:193], v[6:7] op_sel:[1,0,0]
	v_pk_fma_f32 v[122:123], v[26:27], v[194:195], v[122:123] op_sel_hi:[0,1,1]
	v_pk_fma_f32 v[120:121], v[30:31], v[194:195], v[120:121] op_sel_hi:[0,1,1]
	v_pk_fma_f32 v[40:41], v[34:35], v[194:195], v[40:41] op_sel_hi:[0,1,1]
	v_pk_fma_f32 v[22:23], v[38:39], v[194:195], v[22:23] op_sel_hi:[0,1,1]
	v_pk_fma_f32 v[20:21], v[150:151], v[194:195], v[20:21] op_sel_hi:[0,1,1]
	v_pk_fma_f32 v[8:9], v[4:5], v[194:195], v[8:9] op_sel_hi:[0,1,1]
	v_pk_fma_f32 v[16:17], v[12:13], v[194:195], v[16:17] op_sel_hi:[0,1,1]
	v_pk_fma_f32 v[18:19], v[168:169], v[194:195], v[18:19] op_sel_hi:[0,1,1]
	v_pk_fma_f32 v[6:7], v[174:175], v[194:195], v[6:7] op_sel_hi:[0,1,1]
	v_pk_fma_f32 v[122:123], v[26:27], v[196:197], v[122:123] op_sel:[1,0,0]
	v_pk_fma_f32 v[120:121], v[30:31], v[196:197], v[120:121] op_sel:[1,0,0]
	v_pk_fma_f32 v[40:41], v[34:35], v[196:197], v[40:41] op_sel:[1,0,0]
	v_pk_fma_f32 v[22:23], v[38:39], v[196:197], v[22:23] op_sel:[1,0,0]
	v_pk_fma_f32 v[20:21], v[150:151], v[196:197], v[20:21] op_sel:[1,0,0]
	v_pk_fma_f32 v[8:9], v[4:5], v[196:197], v[8:9] op_sel:[1,0,0]
	v_pk_fma_f32 v[16:17], v[12:13], v[196:197], v[16:17] op_sel:[1,0,0]
	v_pk_fma_f32 v[18:19], v[168:169], v[196:197], v[18:19] op_sel:[1,0,0]
	v_pk_fma_f32 v[6:7], v[174:175], v[196:197], v[6:7] op_sel:[1,0,0]
	ds_read_b128 v[24:27], v46 offset:48
	ds_read_b128 v[28:31], v46 offset:8240
	ds_read_b128 v[32:35], v46 offset:16432
	ds_read_b128 v[36:39], v46 offset:24624
	ds_read_b128 v[148:151], v46 offset:32816
	ds_read_b128 v[2:5], v46 offset:41008
	ds_read_b128 v[10:13], v46 offset:49200
	ds_read_b128 v[166:169], v46 offset:57392
	ds_read_b128 v[172:175], v89 offset:48
	s_waitcnt vmcnt(20) lgkmcnt(9)
	v_pk_fma_f32 v[122:123], v[104:105], v[198:199], v[122:123] op_sel_hi:[0,1,1]
	v_pk_fma_f32 v[120:121], v[108:109], v[198:199], v[120:121] op_sel_hi:[0,1,1]
	v_pk_fma_f32 v[40:41], v[112:113], v[198:199], v[40:41] op_sel_hi:[0,1,1]
	v_pk_fma_f32 v[22:23], v[116:117], v[198:199], v[22:23] op_sel_hi:[0,1,1]
	v_pk_fma_f32 v[20:21], v[124:125], v[198:199], v[20:21] op_sel_hi:[0,1,1]
	v_pk_fma_f32 v[8:9], v[128:129], v[198:199], v[8:9] op_sel_hi:[0,1,1]
	v_pk_fma_f32 v[16:17], v[132:133], v[198:199], v[16:17] op_sel_hi:[0,1,1]
	v_pk_fma_f32 v[18:19], v[136:137], v[198:199], v[18:19] op_sel_hi:[0,1,1]
	v_pk_fma_f32 v[6:7], v[140:141], v[198:199], v[6:7] op_sel_hi:[0,1,1]
	v_pk_fma_f32 v[122:123], v[104:105], v[200:201], v[122:123] op_sel:[1,0,0]
	v_pk_fma_f32 v[120:121], v[108:109], v[200:201], v[120:121] op_sel:[1,0,0]
	v_pk_fma_f32 v[40:41], v[112:113], v[200:201], v[40:41] op_sel:[1,0,0]
	v_pk_fma_f32 v[22:23], v[116:117], v[200:201], v[22:23] op_sel:[1,0,0]
	v_pk_fma_f32 v[20:21], v[124:125], v[200:201], v[20:21] op_sel:[1,0,0]
	v_pk_fma_f32 v[8:9], v[128:129], v[200:201], v[8:9] op_sel:[1,0,0]
	v_pk_fma_f32 v[16:17], v[132:133], v[200:201], v[16:17] op_sel:[1,0,0]
	v_pk_fma_f32 v[18:19], v[136:137], v[200:201], v[18:19] op_sel:[1,0,0]
	v_pk_fma_f32 v[6:7], v[140:141], v[200:201], v[6:7] op_sel:[1,0,0]
	v_pk_fma_f32 v[122:123], v[106:107], v[202:203], v[122:123] op_sel_hi:[0,1,1]
	v_pk_fma_f32 v[120:121], v[110:111], v[202:203], v[120:121] op_sel_hi:[0,1,1]
	v_pk_fma_f32 v[40:41], v[114:115], v[202:203], v[40:41] op_sel_hi:[0,1,1]
	v_pk_fma_f32 v[22:23], v[118:119], v[202:203], v[22:23] op_sel_hi:[0,1,1]
	v_pk_fma_f32 v[20:21], v[126:127], v[202:203], v[20:21] op_sel_hi:[0,1,1]
	v_pk_fma_f32 v[8:9], v[130:131], v[202:203], v[8:9] op_sel_hi:[0,1,1]
	v_pk_fma_f32 v[16:17], v[134:135], v[202:203], v[16:17] op_sel_hi:[0,1,1]
	v_pk_fma_f32 v[18:19], v[138:139], v[202:203], v[18:19] op_sel_hi:[0,1,1]
	v_pk_fma_f32 v[6:7], v[142:143], v[202:203], v[6:7] op_sel_hi:[0,1,1]
	v_pk_fma_f32 v[122:123], v[106:107], v[204:205], v[122:123] op_sel:[1,0,0]
	v_pk_fma_f32 v[120:121], v[110:111], v[204:205], v[120:121] op_sel:[1,0,0]
	v_pk_fma_f32 v[40:41], v[114:115], v[204:205], v[40:41] op_sel:[1,0,0]
	v_pk_fma_f32 v[22:23], v[118:119], v[204:205], v[22:23] op_sel:[1,0,0]
	v_pk_fma_f32 v[20:21], v[126:127], v[204:205], v[20:21] op_sel:[1,0,0]
	v_pk_fma_f32 v[8:9], v[130:131], v[204:205], v[8:9] op_sel:[1,0,0]
	v_pk_fma_f32 v[16:17], v[134:135], v[204:205], v[16:17] op_sel:[1,0,0]
	v_pk_fma_f32 v[18:19], v[138:139], v[204:205], v[18:19] op_sel:[1,0,0]
	v_pk_fma_f32 v[6:7], v[142:143], v[204:205], v[6:7] op_sel:[1,0,0]
	ds_read_b128 v[104:107], v46 offset:64
	ds_read_b128 v[108:111], v46 offset:8256
	ds_read_b128 v[112:115], v46 offset:16448
	ds_read_b128 v[116:119], v46 offset:24640
	ds_read_b128 v[124:127], v46 offset:32832
	ds_read_b128 v[128:131], v46 offset:41024
	ds_read_b128 v[132:135], v46 offset:49216
	ds_read_b128 v[136:139], v46 offset:57408
	ds_read_b128 v[140:143], v89 offset:64
	s_waitcnt vmcnt(16) lgkmcnt(9)
; #define LAS __attribute__((address_space(3)))
; __device__ __forceinline__ void phase0(const Params& p, char* shm) {
;     ...
;       for (int k = 0; k < 256; k += 32) {
;         f32x2 w[32];
; #pragma unroll
;         for (int u = 0; u < 32; ++u) w[u] = *(const f32x2*)(W + (size_t)(k + u) * NMOD6);
; #pragma unroll
;         for (int u4 = 0; u4 < 8; ++u4) {
; #pragma unroll
;           for (int r = 0; r < 9; ++r) { const f32x4 cv = *(const LAS f32x4*)(condL + r * 2048 + ks * 256 + k + 4 * u4);
; #pragma unroll
;             for (int e = 0; e < 4; ++e) { a0[r] = fmaf(cv[e], w[4 * u4 + e].x, a0[r]); a1[r] = fmaf(cv[e], w[4 * u4 + e].y, a1[r]); } }
;         }
;       }
	v_pk_fma_f32 v[122:123], v[24:25], v[206:207], v[122:123] op_sel_hi:[0,1,1]
	v_pk_fma_f32 v[120:121], v[28:29], v[206:207], v[120:121] op_sel_hi:[0,1,1]
	v_pk_fma_f32 v[40:41], v[32:33], v[206:207], v[40:41] op_sel_hi:[0,1,1]
	v_pk_fma_f32 v[22:23], v[36:37], v[206:207], v[22:23] op_sel_hi:[0,1,1]
	v_pk_fma_f32 v[20:21], v[148:149], v[206:207], v[20:21] op_sel_hi:[0,1,1]
	v_pk_fma_f32 v[8:9], v[2:3], v[206:207], v[8:9] op_sel_hi:[0,1,1]
	v_pk_fma_f32 v[16:17], v[10:11], v[206:207], v[16:17] op_sel_hi:[0,1,1]
	v_pk_fma_f32 v[18:19], v[166:167], v[206:207], v[18:19] op_sel_hi:[0,1,1]
	v_pk_fma_f32 v[6:7], v[172:173], v[206:207], v[6:7] op_sel_hi:[0,1,1]
	v_pk_fma_f32 v[122:123], v[24:25], v[208:209], v[122:123] op_sel:[1,0,0]
	v_pk_fma_f32 v[120:121], v[28:29], v[208:209], v[120:121] op_sel:[1,0,0]
	v_pk_fma_f32 v[40:41], v[32:33], v[208:209], v[40:41] op_sel:[1,0,0]
	v_pk_fma_f32 v[22:23], v[36:37], v[208:209], v[22:23] op_sel:[1,0,0]
	v_pk_fma_f32 v[20:21], v[148:149], v[208:209], v[20:21] op_sel:[1,0,0]
	v_pk_fma_f32 v[8:9], v[2:3], v[208:209], v[8:9] op_sel:[1,0,0]
	v_pk_fma_f32 v[16:17], v[10:11], v[208:209], v[16:17] op_sel:[1,0,0]
	v_pk_fma_f32 v[18:19], v[166:167], v[208:209], v[18:19] op_sel:[1,0,0]
	v_pk_fma_f32 v[6:7], v[172:173], v[208:209], v[6:7] op_sel:[1,0,0]
	v_pk_fma_f32 v[122:123], v[26:27], v[210:211], v[122:123] op_sel_hi:[0,1,1]
	v_pk_fma_f32 v[120:121], v[30:31], v[210:211], v[120:121] op_sel_hi:[0,1,1]
	v_pk_fma_f32 v[40:41], v[34:35], v[210:211], v[40:41] op_sel_hi:[0,1,1]
	v_pk_fma_f32 v[22:23], v[38:39], v[210:211], v[22:23] op_sel_hi:[0,1,1]
	v_pk_fma_f32 v[20:21], v[150:151], v[210:211], v[20:21] op_sel_hi:[0,1,1]
	v_pk_fma_f32 v[8:9], v[4:5], v[210:211], v[8:9] op_sel_hi:[0,1,1]
	v_pk_fma_f32 v[16:17], v[12:13], v[210:211], v[16:17] op_sel_hi:[0,1,1]
	v_pk_fma_f32 v[18:19], v[168:169], v[210:211], v[18:19] op_sel_hi:[0,1,1]
	v_pk_fma_f32 v[6:7], v[174:175], v[210:211], v[6:7] op_sel_hi:[0,1,1]
	v_pk_fma_f32 v[122:123], v[26:27], v[212:213], v[122:123] op_sel:[1,0,0]
	v_pk_fma_f32 v[120:121], v[30:31], v[212:213], v[120:121] op_sel:[1,0,0]
	v_pk_fma_f32 v[40:41], v[34:35], v[212:213], v[40:41] op_sel:[1,0,0]
	v_pk_fma_f32 v[22:23], v[38:39], v[212:213], v[22:23] op_sel:[1,0,0]
	v_pk_fma_f32 v[20:21], v[150:151], v[212:213], v[20:21] op_sel:[1,0,0]
	v_pk_fma_f32 v[8:9], v[4:5], v[212:213], v[8:9] op_sel:[1,0,0]
	v_pk_fma_f32 v[16:17], v[12:13], v[212:213], v[16:17] op_sel:[1,0,0]
	v_pk_fma_f32 v[18:19], v[168:169], v[212:213], v[18:19] op_sel:[1,0,0]
	v_pk_fma_f32 v[6:7], v[174:175], v[212:213], v[6:7] op_sel:[1,0,0]
	ds_read_b128 v[24:27], v46 offset:80
	ds_read_b128 v[28:31], v46 offset:8272
	ds_read_b128 v[32:35], v46 offset:16464
	ds_read_b128 v[36:39], v46 offset:24656
	ds_read_b128 v[148:151], v46 offset:32848
	ds_read_b128 v[2:5], v46 offset:41040
	ds_read_b128 v[10:13], v46 offset:49232
	ds_read_b128 v[166:169], v46 offset:57424
	ds_read_b128 v[172:175], v89 offset:80
	s_waitcnt vmcnt(12) lgkmcnt(9)
	v_pk_fma_f32 v[122:123], v[104:105], v[214:215], v[122:123] op_sel_hi:[0,1,1]
	v_pk_fma_f32 v[120:121], v[108:109], v[214:215], v[120:121] op_sel_hi:[0,1,1]
	v_pk_fma_f32 v[40:41], v[112:113], v[214:215], v[40:41] op_sel_hi:[0,1,1]
	v_pk_fma_f32 v[22:23], v[116:117], v[214:215], v[22:23] op_sel_hi:[0,1,1]
	v_pk_fma_f32 v[20:21], v[124:125], v[214:215], v[20:21] op_sel_hi:[0,1,1]
	v_pk_fma_f32 v[8:9], v[128:129], v[214:215], v[8:9] op_sel_hi:[0,1,1]
	v_pk_fma_f32 v[16:17], v[132:133], v[214:215], v[16:17] op_sel_hi:[0,1,1]
	v_pk_fma_f32 v[18:19], v[136:137], v[214:215], v[18:19] op_sel_hi:[0,1,1]
	v_pk_fma_f32 v[6:7], v[140:141], v[214:215], v[6:7] op_sel_hi:[0,1,1]
	v_pk_fma_f32 v[122:123], v[104:105], v[216:217], v[122:123] op_sel:[1,0,0]
	v_pk_fma_f32 v[120:121], v[108:109], v[216:217], v[120:121] op_sel:[1,0,0]
	v_pk_fma_f32 v[40:41], v[112:113], v[216:217], v[40:41] op_sel:[1,0,0]
	v_pk_fma_f32 v[22:23], v[116:117], v[216:217], v[22:23] op_sel:[1,0,0]
	v_pk_fma_f32 v[20:21], v[124:125], v[216:217], v[20:21] op_sel:[1,0,0]
	v_pk_fma_f32 v[8:9], v[128:129], v[216:217], v[8:9] op_sel:[1,0,0]
	v_pk_fma_f32 v[16:17], v[132:133], v[216:217], v[16:17] op_sel:[1,0,0]
	v_pk_fma_f32 v[18:19], v[136:137], v[216:217], v[18:19] op_sel:[1,0,0]
	v_pk_fma_f32 v[6:7], v[140:141], v[216:217], v[6:7] op_sel:[1,0,0]
	v_pk_fma_f32 v[122:123], v[106:107], v[218:219], v[122:123] op_sel_hi:[0,1,1]
	v_pk_fma_f32 v[120:121], v[110:111], v[218:219], v[120:121] op_sel_hi:[0,1,1]
	v_pk_fma_f32 v[40:41], v[114:115], v[218:219], v[40:41] op_sel_hi:[0,1,1]
	v_pk_fma_f32 v[22:23], v[118:119], v[218:219], v[22:23] op_sel_hi:[0,1,1]
	v_pk_fma_f32 v[20:21], v[126:127], v[218:219], v[20:21] op_sel_hi:[0,1,1]
	v_pk_fma_f32 v[8:9], v[130:131], v[218:219], v[8:9] op_sel_hi:[0,1,1]
	v_pk_fma_f32 v[16:17], v[134:135], v[218:219], v[16:17] op_sel_hi:[0,1,1]
	v_pk_fma_f32 v[18:19], v[138:139], v[218:219], v[18:19] op_sel_hi:[0,1,1]
	v_pk_fma_f32 v[6:7], v[142:143], v[218:219], v[6:7] op_sel_hi:[0,1,1]
	v_pk_fma_f32 v[122:123], v[106:107], v[220:221], v[122:123] op_sel:[1,0,0]
	v_pk_fma_f32 v[120:121], v[110:111], v[220:221], v[120:121] op_sel:[1,0,0]
	v_pk_fma_f32 v[40:41], v[114:115], v[220:221], v[40:41] op_sel:[1,0,0]
	v_pk_fma_f32 v[22:23], v[118:119], v[220:221], v[22:23] op_sel:[1,0,0]
	v_pk_fma_f32 v[20:21], v[126:127], v[220:221], v[20:21] op_sel:[1,0,0]
	v_pk_fma_f32 v[8:9], v[130:131], v[220:221], v[8:9] op_sel:[1,0,0]
	v_pk_fma_f32 v[16:17], v[134:135], v[220:221], v[16:17] op_sel:[1,0,0]
	v_pk_fma_f32 v[18:19], v[138:139], v[220:221], v[18:19] op_sel:[1,0,0]
	v_pk_fma_f32 v[6:7], v[142:143], v[220:221], v[6:7] op_sel:[1,0,0]
	ds_read_b128 v[104:107], v46 offset:96
	ds_read_b128 v[108:111], v46 offset:8288
	ds_read_b128 v[112:115], v46 offset:16480
	ds_read_b128 v[116:119], v46 offset:24672
	ds_read_b128 v[124:127], v46 offset:32864
	ds_read_b128 v[128:131], v46 offset:41056
	ds_read_b128 v[132:135], v46 offset:49248
	ds_read_b128 v[136:139], v46 offset:57440
	ds_read_b128 v[140:143], v89 offset:96
	s_waitcnt vmcnt(8) lgkmcnt(9)
; #define LAS __attribute__((address_space(3)))
; __device__ __forceinline__ void phase0(const Params& p, char* shm) {
;     ...
;       for (int k = 0; k < 256; k += 32) {
;         f32x2 w[32];
; #pragma unroll
;         for (int u = 0; u < 32; ++u) w[u] = *(const f32x2*)(W + (size_t)(k + u) * NMOD6);
; #pragma unroll
;         for (int u4 = 0; u4 < 8; ++u4) {
; #pragma unroll
;           for (int r = 0; r < 9; ++r) { const f32x4 cv = *(const LAS f32x4*)(condL + r * 2048 + ks * 256 + k + 4 * u4);
; #pragma unroll
;             for (int e = 0; e < 4; ++e) { a0[r] = fmaf(cv[e], w[4 * u4 + e].x, a0[r]); a1[r] = fmaf(cv[e], w[4 * u4 + e].y, a1[r]); } }
;         }
;       }
	v_pk_fma_f32 v[122:123], v[24:25], v[222:223], v[122:123] op_sel_hi:[0,1,1]
	v_pk_fma_f32 v[120:121], v[28:29], v[222:223], v[120:121] op_sel_hi:[0,1,1]
	v_pk_fma_f32 v[40:41], v[32:33], v[222:223], v[40:41] op_sel_hi:[0,1,1]
	v_pk_fma_f32 v[22:23], v[36:37], v[222:223], v[22:23] op_sel_hi:[0,1,1]
	v_pk_fma_f32 v[20:21], v[148:149], v[222:223], v[20:21] op_sel_hi:[0,1,1]
	v_pk_fma_f32 v[8:9], v[2:3], v[222:223], v[8:9] op_sel_hi:[0,1,1]
	v_pk_fma_f32 v[16:17], v[10:11], v[222:223], v[16:17] op_sel_hi:[0,1,1]
	v_pk_fma_f32 v[18:19], v[166:167], v[222:223], v[18:19] op_sel_hi:[0,1,1]
	v_pk_fma_f32 v[6:7], v[172:173], v[222:223], v[6:7] op_sel_hi:[0,1,1]
	v_pk_fma_f32 v[122:123], v[24:25], v[224:225], v[122:123] op_sel:[1,0,0]
	v_pk_fma_f32 v[120:121], v[28:29], v[224:225], v[120:121] op_sel:[1,0,0]
	v_pk_fma_f32 v[40:41], v[32:33], v[224:225], v[40:41] op_sel:[1,0,0]
	v_pk_fma_f32 v[22:23], v[36:37], v[224:225], v[22:23] op_sel:[1,0,0]
	v_pk_fma_f32 v[20:21], v[148:149], v[224:225], v[20:21] op_sel:[1,0,0]
	v_pk_fma_f32 v[8:9], v[2:3], v[224:225], v[8:9] op_sel:[1,0,0]
	v_pk_fma_f32 v[16:17], v[10:11], v[224:225], v[16:17] op_sel:[1,0,0]
	v_pk_fma_f32 v[18:19], v[166:167], v[224:225], v[18:19] op_sel:[1,0,0]
	v_pk_fma_f32 v[6:7], v[172:173], v[224:225], v[6:7] op_sel:[1,0,0]
	v_pk_fma_f32 v[122:123], v[26:27], v[226:227], v[122:123] op_sel_hi:[0,1,1]
	v_pk_fma_f32 v[120:121], v[30:31], v[226:227], v[120:121] op_sel_hi:[0,1,1]
	v_pk_fma_f32 v[40:41], v[34:35], v[226:227], v[40:41] op_sel_hi:[0,1,1]
	v_pk_fma_f32 v[22:23], v[38:39], v[226:227], v[22:23] op_sel_hi:[0,1,1]
	v_pk_fma_f32 v[20:21], v[150:151], v[226:227], v[20:21] op_sel_hi:[0,1,1]
	v_pk_fma_f32 v[8:9], v[4:5], v[226:227], v[8:9] op_sel_hi:[0,1,1]
	v_pk_fma_f32 v[16:17], v[12:13], v[226:227], v[16:17] op_sel_hi:[0,1,1]
	v_pk_fma_f32 v[18:19], v[168:169], v[226:227], v[18:19] op_sel_hi:[0,1,1]
	v_pk_fma_f32 v[6:7], v[174:175], v[226:227], v[6:7] op_sel_hi:[0,1,1]
	v_pk_fma_f32 v[122:123], v[26:27], v[228:229], v[122:123] op_sel:[1,0,0]
	v_pk_fma_f32 v[120:121], v[30:31], v[228:229], v[120:121] op_sel:[1,0,0]
	v_pk_fma_f32 v[40:41], v[34:35], v[228:229], v[40:41] op_sel:[1,0,0]
	v_pk_fma_f32 v[22:23], v[38:39], v[228:229], v[22:23] op_sel:[1,0,0]
	v_pk_fma_f32 v[20:21], v[150:151], v[228:229], v[20:21] op_sel:[1,0,0]
	v_pk_fma_f32 v[8:9], v[4:5], v[228:229], v[8:9] op_sel:[1,0,0]
	v_pk_fma_f32 v[16:17], v[12:13], v[228:229], v[16:17] op_sel:[1,0,0]
	v_pk_fma_f32 v[18:19], v[168:169], v[228:229], v[18:19] op_sel:[1,0,0]
	v_pk_fma_f32 v[6:7], v[174:175], v[228:229], v[6:7] op_sel:[1,0,0]
	ds_read_b128 v[24:27], v46 offset:112
	ds_read_b128 v[28:31], v46 offset:8304
	ds_read_b128 v[32:35], v46 offset:16496
	ds_read_b128 v[36:39], v46 offset:24688
	ds_read_b128 v[148:151], v46 offset:32880
	ds_read_b128 v[2:5], v46 offset:41072
	ds_read_b128 v[10:13], v46 offset:49264
	ds_read_b128 v[166:169], v46 offset:57456
	ds_read_b128 v[172:175], v89 offset:112
	s_waitcnt vmcnt(4) lgkmcnt(9)
	v_pk_fma_f32 v[122:123], v[104:105], v[230:231], v[122:123] op_sel_hi:[0,1,1]
	v_pk_fma_f32 v[120:121], v[108:109], v[230:231], v[120:121] op_sel_hi:[0,1,1]
	v_pk_fma_f32 v[40:41], v[112:113], v[230:231], v[40:41] op_sel_hi:[0,1,1]
	v_pk_fma_f32 v[22:23], v[116:117], v[230:231], v[22:23] op_sel_hi:[0,1,1]
	v_pk_fma_f32 v[20:21], v[124:125], v[230:231], v[20:21] op_sel_hi:[0,1,1]
	v_pk_fma_f32 v[8:9], v[128:129], v[230:231], v[8:9] op_sel_hi:[0,1,1]
	v_pk_fma_f32 v[16:17], v[132:133], v[230:231], v[16:17] op_sel_hi:[0,1,1]
	v_pk_fma_f32 v[18:19], v[136:137], v[230:231], v[18:19] op_sel_hi:[0,1,1]
	v_pk_fma_f32 v[6:7], v[140:141], v[230:231], v[6:7] op_sel_hi:[0,1,1]
	v_pk_fma_f32 v[122:123], v[104:105], v[232:233], v[122:123] op_sel:[1,0,0]
	v_pk_fma_f32 v[120:121], v[108:109], v[232:233], v[120:121] op_sel:[1,0,0]
	v_pk_fma_f32 v[40:41], v[112:113], v[232:233], v[40:41] op_sel:[1,0,0]
	v_pk_fma_f32 v[22:23], v[116:117], v[232:233], v[22:23] op_sel:[1,0,0]
	v_pk_fma_f32 v[20:21], v[124:125], v[232:233], v[20:21] op_sel:[1,0,0]
	v_pk_fma_f32 v[8:9], v[128:129], v[232:233], v[8:9] op_sel:[1,0,0]
	v_pk_fma_f32 v[16:17], v[132:133], v[232:233], v[16:17] op_sel:[1,0,0]
	v_pk_fma_f32 v[18:19], v[136:137], v[232:233], v[18:19] op_sel:[1,0,0]
	v_pk_fma_f32 v[6:7], v[140:141], v[232:233], v[6:7] op_sel:[1,0,0]
	v_pk_fma_f32 v[122:123], v[106:107], v[234:235], v[122:123] op_sel_hi:[0,1,1]
	v_pk_fma_f32 v[120:121], v[110:111], v[234:235], v[120:121] op_sel_hi:[0,1,1]
	v_pk_fma_f32 v[40:41], v[114:115], v[234:235], v[40:41] op_sel_hi:[0,1,1]
	v_pk_fma_f32 v[22:23], v[118:119], v[234:235], v[22:23] op_sel_hi:[0,1,1]
	v_pk_fma_f32 v[20:21], v[126:127], v[234:235], v[20:21] op_sel_hi:[0,1,1]
	v_pk_fma_f32 v[8:9], v[130:131], v[234:235], v[8:9] op_sel_hi:[0,1,1]
	v_pk_fma_f32 v[16:17], v[134:135], v[234:235], v[16:17] op_sel_hi:[0,1,1]
	v_pk_fma_f32 v[18:19], v[138:139], v[234:235], v[18:19] op_sel_hi:[0,1,1]
	v_pk_fma_f32 v[6:7], v[142:143], v[234:235], v[6:7] op_sel_hi:[0,1,1]
	v_pk_fma_f32 v[122:123], v[106:107], v[236:237], v[122:123] op_sel:[1,0,0]
	v_pk_fma_f32 v[120:121], v[110:111], v[236:237], v[120:121] op_sel:[1,0,0]
	v_pk_fma_f32 v[40:41], v[114:115], v[236:237], v[40:41] op_sel:[1,0,0]
	v_pk_fma_f32 v[22:23], v[118:119], v[236:237], v[22:23] op_sel:[1,0,0]
	v_pk_fma_f32 v[20:21], v[126:127], v[236:237], v[20:21] op_sel:[1,0,0]
	v_pk_fma_f32 v[8:9], v[130:131], v[236:237], v[8:9] op_sel:[1,0,0]
	v_pk_fma_f32 v[16:17], v[134:135], v[236:237], v[16:17] op_sel:[1,0,0]
	v_pk_fma_f32 v[18:19], v[138:139], v[236:237], v[18:19] op_sel:[1,0,0]
	v_pk_fma_f32 v[6:7], v[142:143], v[236:237], v[6:7] op_sel:[1,0,0]
	s_waitcnt vmcnt(0) lgkmcnt(0)
; #define LAS __attribute__((address_space(3)))
; __device__ __forceinline__ void phase0(const Params& p, char* shm) {
;     ...
;         for (int u4 = 0; u4 < 8; ++u4) {
; #pragma unroll
;           for (int r = 0; r < 9; ++r) { const f32x4 cv = *(const LAS f32x4*)(condL + r * 2048 + ks * 256 + k + 4 * u4);
; #pragma unroll
;             for (int e = 0; e < 4; ++e) { a0[r] = fmaf(cv[e], w[4 * u4 + e].x, a0[r]); a1[r] = fmaf(cv[e], w[4 * u4 + e].y, a1[r]); } }
;         }
;       }
; #pragma unroll
;       for (int r = 0; r < 9; ++r) { red[(ks * 9 + r) * 128 + cp] = a0[r]; red[(ks * 9 + r) * 128 + cp + 1] = a1[r]; }
;       __syncthreads();
;       float* modv = (float*)(p.ws + OFF_MODV);
;       for (int i = tid; i < 9 * 128; i += 512) { const int r = i >> 7, c = i & 127; float s = 0.f;
	v_pk_fma_f32 v[122:123], v[24:25], v[238:239], v[122:123] op_sel_hi:[0,1,1]
	v_pk_fma_f32 v[120:121], v[28:29], v[238:239], v[120:121] op_sel_hi:[0,1,1]
	v_pk_fma_f32 v[40:41], v[32:33], v[238:239], v[40:41] op_sel_hi:[0,1,1]
	v_pk_fma_f32 v[22:23], v[36:37], v[238:239], v[22:23] op_sel_hi:[0,1,1]
	v_pk_fma_f32 v[20:21], v[148:149], v[238:239], v[20:21] op_sel_hi:[0,1,1]
	v_pk_fma_f32 v[8:9], v[2:3], v[238:239], v[8:9] op_sel_hi:[0,1,1]
	v_pk_fma_f32 v[16:17], v[10:11], v[238:239], v[16:17] op_sel_hi:[0,1,1]
	v_pk_fma_f32 v[18:19], v[166:167], v[238:239], v[18:19] op_sel_hi:[0,1,1]
	v_pk_fma_f32 v[6:7], v[172:173], v[238:239], v[6:7] op_sel_hi:[0,1,1]
	v_pk_fma_f32 v[122:123], v[24:25], v[240:241], v[122:123] op_sel:[1,0,0]
	v_pk_fma_f32 v[120:121], v[28:29], v[240:241], v[120:121] op_sel:[1,0,0]
	v_pk_fma_f32 v[40:41], v[32:33], v[240:241], v[40:41] op_sel:[1,0,0]
	v_pk_fma_f32 v[22:23], v[36:37], v[240:241], v[22:23] op_sel:[1,0,0]
	v_pk_fma_f32 v[20:21], v[148:149], v[240:241], v[20:21] op_sel:[1,0,0]
	v_pk_fma_f32 v[8:9], v[2:3], v[240:241], v[8:9] op_sel:[1,0,0]
	v_pk_fma_f32 v[16:17], v[10:11], v[240:241], v[16:17] op_sel:[1,0,0]
	v_pk_fma_f32 v[18:19], v[166:167], v[240:241], v[18:19] op_sel:[1,0,0]
	v_pk_fma_f32 v[6:7], v[172:173], v[240:241], v[6:7] op_sel:[1,0,0]
	v_pk_fma_f32 v[122:123], v[26:27], v[242:243], v[122:123] op_sel_hi:[0,1,1]
	v_pk_fma_f32 v[120:121], v[30:31], v[242:243], v[120:121] op_sel_hi:[0,1,1]
	v_pk_fma_f32 v[40:41], v[34:35], v[242:243], v[40:41] op_sel_hi:[0,1,1]
	v_pk_fma_f32 v[22:23], v[38:39], v[242:243], v[22:23] op_sel_hi:[0,1,1]
	v_pk_fma_f32 v[20:21], v[150:151], v[242:243], v[20:21] op_sel_hi:[0,1,1]
	v_pk_fma_f32 v[8:9], v[4:5], v[242:243], v[8:9] op_sel_hi:[0,1,1]
	v_pk_fma_f32 v[16:17], v[12:13], v[242:243], v[16:17] op_sel_hi:[0,1,1]
	v_pk_fma_f32 v[18:19], v[168:169], v[242:243], v[18:19] op_sel_hi:[0,1,1]
	v_pk_fma_f32 v[6:7], v[174:175], v[242:243], v[6:7] op_sel_hi:[0,1,1]
	v_pk_fma_f32 v[122:123], v[26:27], v[244:245], v[122:123] op_sel:[1,0,0]
	v_pk_fma_f32 v[120:121], v[30:31], v[244:245], v[120:121] op_sel:[1,0,0]
	v_pk_fma_f32 v[40:41], v[34:35], v[244:245], v[40:41] op_sel:[1,0,0]
	v_pk_fma_f32 v[22:23], v[38:39], v[244:245], v[22:23] op_sel:[1,0,0]
	v_pk_fma_f32 v[20:21], v[150:151], v[244:245], v[20:21] op_sel:[1,0,0]
	v_pk_fma_f32 v[8:9], v[4:5], v[244:245], v[8:9] op_sel:[1,0,0]
	v_pk_fma_f32 v[16:17], v[12:13], v[244:245], v[16:17] op_sel:[1,0,0]
	v_pk_fma_f32 v[18:19], v[168:169], v[244:245], v[18:19] op_sel:[1,0,0]
	v_pk_fma_f32 v[6:7], v[174:175], v[244:245], v[6:7] op_sel:[1,0,0]
	ds_write2st64_b64 v97, v[122:123], v[120:121] offset1:1
	ds_write2st64_b64 v97, v[40:41], v[22:23] offset0:2 offset1:3
	ds_write2st64_b64 v97, v[20:21], v[8:9] offset0:4 offset1:5
	ds_write2st64_b64 v97, v[16:17], v[18:19] offset0:6 offset1:7
	ds_write_b64 v97, v[6:7] offset:4096
	s_waitcnt lgkmcnt(0)
	s_barrier
	s_and_saveexec_b64 s[24:25], s[12:13]
	s_cbranch_execz .LBB0_6
	s_mul_i32 s1, s20, 0xc000
	s_mul_hi_i32 s0, s20, 0xc000
	s_add_u32 s21, s48, s1
	s_addc_u32 s26, s49, s0
	s_lshl_b64 s[0:1], s[22:23], 2
	s_add_u32 s22, s21, s0
	s_addc_u32 s23, s26, s1
	v_mov_b32_e32 v99, v47
	s_mul_hi_i32 s21, s20, 9
	s_mul_i32 s20, s20, 9
	v_lshl_add_u64 v[2:3], s[22:23], 0, v[98:99]
	v_lshl_add_u64 v[4:5], v[82:83], 0, s[0:1]
	s_mov_b64 s[22:23], 0
	v_mov_b32_e32 v6, v42
